# speedup vs baseline: 1.0142x; 1.0142x over previous
.LBB0_353:
	s_or_b64 exec, exec, s[20:21]
	s_mulk_i32 s17, 0xffa0
	s_add_i32 s17, s17, s55
	s_lshl_b32 s17, s17, 5
	s_and_b32 s20, s17, 0xffffff00
	s_ashr_i32 s21, s20, 31
	s_lshl_b64 s[56:57], s[20:21], 11
	s_add_u32 s56, s24, s56
	s_addc_u32 s57, s25, s57
	s_mov_b64 s[58:59], s[56:57]
	s_mov_b32 m0, s28
	s_ashr_i32 s19, s18, 31
	global_load_lds_dwordx4 v130, s[58:59]
	v_lshl_add_u64 v[134:135], s[58:59], 0, v[132:133]
	s_lshl_b64 s[58:59], s[18:19], 11
	s_add_u32 s58, s22, s58
	s_addc_u32 s59, s23, s59
	s_bitset1_b32 s20, 7
	s_ashr_i32 s21, s20, 31
	s_lshl_b64 s[20:21], s[20:21], 11
	s_add_u32 s20, s24, s20
	s_addc_u32 s21, s25, s21
	s_bitset1_b32 s18, 7
	s_mov_b32 m0, s29
	s_mov_b64 s[60:61], s[58:59]
	s_ashr_i32 s19, s18, 31
	global_load_lds_dwordx4 v[134:135], off
	s_mov_b32 m0, s27
	v_lshl_add_u64 v[134:135], s[60:61], 0, v[130:131]
	s_lshl_b64 s[18:19], s[18:19], 11
	global_load_lds_dwordx4 v[134:135], off
	v_lshl_add_u64 v[134:135], s[60:61], 0, v[132:133]
	s_mov_b32 m0, s30
	s_mov_b64 s[60:61], s[20:21]
	s_add_u32 s18, s22, s18
	global_load_lds_dwordx4 v[134:135], off
	s_mov_b32 m0, s31
	v_lshl_add_u64 v[134:135], s[60:61], 0, v[130:131]
	s_addc_u32 s19, s23, s19
	global_load_lds_dwordx4 v[134:135], off
	v_lshl_add_u64 v[134:135], s[60:61], 0, v[132:133]
	s_mov_b32 m0, s33
	s_mov_b64 s[60:61], s[18:19]
	global_load_lds_dwordx4 v[134:135], off
	s_mov_b32 m0, s34
	v_lshl_add_u64 v[134:135], s[60:61], 0, v[130:131]
	s_add_u32 s56, s56, 0x80
	global_load_lds_dwordx4 v[134:135], off
	v_lshl_add_u64 v[134:135], s[60:61], 0, v[132:133]
	s_mov_b32 m0, s35
	s_addc_u32 s57, s57, 0
	global_load_lds_dwordx4 v[134:135], off
	s_mov_b32 m0, s36
	global_load_lds_dwordx4 v130, s[56:57]
	v_lshl_add_u64 v[134:135], s[56:57], 0, v[132:133]
	s_add_u32 s56, s58, 0x80
	s_mov_b32 m0, s37
	s_addc_u32 s57, s59, 0
	global_load_lds_dwordx4 v[134:135], off
	s_mov_b32 m0, s38
	v_lshl_add_u64 v[134:135], s[56:57], 0, v[130:131]
	s_add_u32 s20, s20, 0x80
	global_load_lds_dwordx4 v[134:135], off
	v_lshl_add_u64 v[134:135], s[56:57], 0, v[132:133]
	s_mov_b32 m0, s39
	s_addc_u32 s21, s21, 0
	global_load_lds_dwordx4 v[134:135], off
	s_mov_b32 m0, s40
	v_lshl_add_u64 v[134:135], s[20:21], 0, v[130:131]
	s_add_u32 s18, s18, 0x80
	global_load_lds_dwordx4 v[134:135], off
	v_lshl_add_u64 v[134:135], s[20:21], 0, v[132:133]
	s_mov_b32 m0, s41
	s_addc_u32 s19, s19, 0
	global_load_lds_dwordx4 v[134:135], off
	s_mov_b32 m0, s42
	global_load_lds_dwordx4 v130, s[18:19]
	s_mov_b32 m0, s43
	s_nop 0
	global_load_lds_dwordx4 v132, s[18:19]

.LBB0_363:
	s_mul_hi_i32 s12, s55, 0x2aaaaaab
	s_lshr_b32 s13, s12, 31
	s_ashr_i32 s12, s12, 4
	s_add_i32 s12, s12, s13
	s_lshl_b32 s14, s55, 8
	s_mul_i32 s13, s12, 0xffffffa0
	s_lshl_b32 s12, s12, 11
	s_and_b32 s14, s14, 0x700
	s_or_b32 s16, s12, s14
	s_add_i32 s13, s13, s55
	s_or_b32 s18, s16, 0x80
	s_lshl_b32 s12, s13, 5
	s_ashr_i32 s19, s18, 31
	s_and_b32 s12, s12, 0xffffff00
	s_lshl_b64 s[14:15], s[18:19], 10
	s_lshl_b64 s[18:19], s[18:19], 11
	s_add_u32 s20, s22, s18
	s_addc_u32 s21, s23, s19
	s_ashr_i32 s13, s12, 31
	s_lshl_b64 s[18:19], s[12:13], 11
	s_add_u32 s56, s24, s18
	s_addc_u32 s57, s25, s19
	s_ashr_i32 s17, s16, 31
	s_barrier
	s_barrier
	s_lshl_b64 s[18:19], s[16:17], 11
	ds_read_b128 v[2:5], v137
	ds_read_b128 v[6:9], v137 offset:1024
	ds_read_b128 v[10:13], v137 offset:2048
	ds_read_b128 v[14:17], v137 offset:3072
	s_add_u32 s17, s22, s18
	s_addc_u32 s58, s23, s19
	s_or_b32 s18, s12, 0x80
	s_ashr_i32 s19, s18, 31
	s_lshl_b64 s[18:19], s[18:19], 11
	s_add_u32 s59, s24, s18
	s_addc_u32 s60, s25, s19
	ds_read_b128 v[18:21], v136 offset:7168
	ds_read_b128 v[22:25], v136 offset:6144
	ds_read_b128 v[26:29], v136 offset:5120
	ds_read_b128 v[30:33], v136 offset:4096
	ds_read_b128 v[34:37], v136 offset:3072
	ds_read_b128 v[38:41], v136 offset:2048
	ds_read_b128 v[42:45], v136 offset:1024
	ds_read_b128 v[46:49], v136
	s_waitcnt lgkmcnt(8)
	s_barrier
	s_waitcnt lgkmcnt(0)
	s_setprio 3
	s_waitcnt lgkmcnt(0)
	v_mfma_f32_16x16x32_bf16 v[50:53], v[46:49], v[2:5], 0
	v_mfma_f32_16x16x32_bf16 v[54:57], v[46:49], v[10:13], 0
	v_mfma_f32_16x16x32_bf16 v[58:61], v[38:41], v[2:5], 0
	v_mfma_f32_16x16x32_bf16 v[62:65], v[38:41], v[10:13], 0
	v_mfma_f32_16x16x32_bf16 v[66:69], v[30:33], v[2:5], 0
	v_mfma_f32_16x16x32_bf16 v[70:73], v[30:33], v[10:13], 0
	v_mfma_f32_16x16x32_bf16 v[74:77], v[22:25], v[2:5], 0
	v_mfma_f32_16x16x32_bf16 v[78:81], v[22:25], v[10:13], 0
	v_mfma_f32_16x16x32_bf16 v[50:53], v[42:45], v[6:9], v[50:53]
	v_mfma_f32_16x16x32_bf16 v[54:57], v[42:45], v[14:17], v[54:57]
	v_mfma_f32_16x16x32_bf16 v[58:61], v[34:37], v[6:9], v[58:61]
	v_mfma_f32_16x16x32_bf16 v[62:65], v[34:37], v[14:17], v[62:65]
	v_mfma_f32_16x16x32_bf16 v[66:69], v[26:29], v[6:9], v[66:69]
	v_mfma_f32_16x16x32_bf16 v[70:73], v[26:29], v[14:17], v[70:73]
	v_mfma_f32_16x16x32_bf16 v[74:77], v[18:21], v[6:9], v[74:77]
	v_mfma_f32_16x16x32_bf16 v[78:81], v[18:21], v[14:17], v[78:81]
	s_setprio 0
	s_barrier
	s_add_u32 s18, s56, 0x100
	s_addc_u32 s19, s57, 0
	s_mov_b32 m0, s28
	ds_read_b128 v[82:85], v137 offset:16384
	ds_read_b128 v[86:89], v137 offset:17408
	ds_read_b128 v[90:93], v137 offset:18432
	ds_read_b128 v[94:97], v137 offset:19456
	s_nop 0
	global_load_lds_dwordx4 v130, s[18:19]
	s_mov_b32 m0, s29
	s_nop 0
	global_load_lds_dwordx4 v132, s[18:19]
	s_barrier
	s_waitcnt lgkmcnt(0)
	s_setprio 3
	s_waitcnt lgkmcnt(0)
	v_mfma_f32_16x16x32_bf16 v[98:101], v[46:49], v[82:85], 0
	v_mfma_f32_16x16x32_bf16 v[46:49], v[46:49], v[90:93], 0
	v_mfma_f32_16x16x32_bf16 v[98:101], v[42:45], v[86:89], v[98:101]
	v_mfma_f32_16x16x32_bf16 v[42:45], v[42:45], v[94:97], v[46:49]
	v_mfma_f32_16x16x32_bf16 v[46:49], v[38:41], v[82:85], 0
	v_mfma_f32_16x16x32_bf16 v[38:41], v[38:41], v[90:93], 0
	v_mfma_f32_16x16x32_bf16 v[46:49], v[34:37], v[86:89], v[46:49]
	v_mfma_f32_16x16x32_bf16 v[34:37], v[34:37], v[94:97], v[38:41]
	v_mfma_f32_16x16x32_bf16 v[38:41], v[30:33], v[82:85], 0
	v_mfma_f32_16x16x32_bf16 v[30:33], v[30:33], v[90:93], 0
	v_mfma_f32_16x16x32_bf16 v[38:41], v[26:29], v[86:89], v[38:41]
	v_mfma_f32_16x16x32_bf16 v[102:105], v[26:29], v[94:97], v[30:33]
	v_mfma_f32_16x16x32_bf16 v[26:29], v[22:25], v[82:85], 0
	v_mfma_f32_16x16x32_bf16 v[22:25], v[22:25], v[90:93], 0
	v_mfma_f32_16x16x32_bf16 v[106:109], v[18:21], v[86:89], v[26:29]
	v_mfma_f32_16x16x32_bf16 v[110:113], v[18:21], v[94:97], v[22:25]
	s_setprio 0
	s_add_u32 s18, s17, 0x100
	s_addc_u32 s19, s58, 0
	s_mov_b32 m0, s27
	s_barrier
	ds_read_b128 v[18:21], v136 offset:16384
	ds_read_b128 v[22:25], v136 offset:17408
	ds_read_b128 v[26:29], v136 offset:18432
	ds_read_b128 v[30:33], v136 offset:19456
	ds_read_b128 v[114:117], v136 offset:20480
	ds_read_b128 v[118:121], v136 offset:21504
	ds_read_b128 v[122:125], v136 offset:22528
	ds_read_b128 v[126:129], v136 offset:23552
	s_nop 0
	global_load_lds_dwordx4 v130, s[18:19]
	s_mov_b32 m0, s30
	s_nop 0
	global_load_lds_dwordx4 v132, s[18:19]
	s_barrier
	s_waitcnt lgkmcnt(0)
	s_setprio 3
	s_waitcnt lgkmcnt(0)
	v_mfma_f32_16x16x32_bf16 v[142:145], v[18:21], v[2:5], 0
	v_mfma_f32_16x16x32_bf16 v[150:153], v[26:29], v[2:5], 0
	v_mfma_f32_16x16x32_bf16 v[158:161], v[114:117], v[2:5], 0
	v_mfma_f32_16x16x32_bf16 v[2:5], v[122:125], v[2:5], 0
	v_mfma_f32_16x16x32_bf16 v[146:149], v[18:21], v[10:13], 0
	v_mfma_f32_16x16x32_bf16 v[154:157], v[26:29], v[10:13], 0
	v_mfma_f32_16x16x32_bf16 v[162:165], v[114:117], v[10:13], 0
	v_mfma_f32_16x16x32_bf16 v[166:169], v[126:129], v[6:9], v[2:5]
	v_mfma_f32_16x16x32_bf16 v[2:5], v[122:125], v[10:13], 0
	v_mfma_f32_16x16x32_bf16 v[142:145], v[22:25], v[6:9], v[142:145]
	v_mfma_f32_16x16x32_bf16 v[146:149], v[22:25], v[14:17], v[146:149]
	v_mfma_f32_16x16x32_bf16 v[150:153], v[30:33], v[6:9], v[150:153]
	v_mfma_f32_16x16x32_bf16 v[154:157], v[30:33], v[14:17], v[154:157]
	v_mfma_f32_16x16x32_bf16 v[158:161], v[118:121], v[6:9], v[158:161]
	v_mfma_f32_16x16x32_bf16 v[162:165], v[118:121], v[14:17], v[162:165]
	v_mfma_f32_16x16x32_bf16 v[170:173], v[126:129], v[14:17], v[2:5]
	s_setprio 0
	s_barrier
	s_add_u32 s18, s59, 0x100
	s_addc_u32 s19, s60, 0
	s_mov_b32 m0, s31
	s_nop 0
	global_load_lds_dwordx4 v130, s[18:19]
	s_mov_b32 m0, s33
	s_nop 0
	global_load_lds_dwordx4 v132, s[18:19]
	s_waitcnt vmcnt(22)
	s_barrier
	s_setprio 3
	v_mfma_f32_16x16x32_bf16 v[2:5], v[18:21], v[82:85], 0
	v_mfma_f32_16x16x32_bf16 v[174:177], v[22:25], v[86:89], v[2:5]
	v_mfma_f32_16x16x32_bf16 v[2:5], v[18:21], v[90:93], 0
	v_mfma_f32_16x16x32_bf16 v[178:181], v[22:25], v[94:97], v[2:5]
	v_mfma_f32_16x16x32_bf16 v[2:5], v[26:29], v[82:85], 0
	v_mfma_f32_16x16x32_bf16 v[182:185], v[30:33], v[86:89], v[2:5]
	v_mfma_f32_16x16x32_bf16 v[2:5], v[26:29], v[90:93], 0
	v_mfma_f32_16x16x32_bf16 v[186:189], v[30:33], v[94:97], v[2:5]
	v_mfma_f32_16x16x32_bf16 v[2:5], v[114:117], v[82:85], 0
	v_mfma_f32_16x16x32_bf16 v[190:193], v[118:121], v[86:89], v[2:5]
	v_mfma_f32_16x16x32_bf16 v[2:5], v[114:117], v[90:93], 0
	v_mfma_f32_16x16x32_bf16 v[194:197], v[118:121], v[94:97], v[2:5]
	v_mfma_f32_16x16x32_bf16 v[2:5], v[122:125], v[82:85], 0
	v_mfma_f32_16x16x32_bf16 v[198:201], v[126:129], v[86:89], v[2:5]
	v_mfma_f32_16x16x32_bf16 v[2:5], v[122:125], v[90:93], 0
	v_mfma_f32_16x16x32_bf16 v[202:205], v[126:129], v[94:97], v[2:5]
	s_setprio 0
	s_barrier
	ds_read_b128 v[114:117], v137 offset:32768
	ds_read_b128 v[118:121], v137 offset:33792
	ds_read_b128 v[122:125], v137 offset:34816
	ds_read_b128 v[126:129], v137 offset:35840
	s_add_u32 s18, s20, 0x100
	s_addc_u32 s19, s21, 0
	s_mov_b32 m0, s34
	ds_read_b128 v[82:85], v136 offset:32768
	ds_read_b128 v[86:89], v136 offset:33792
	ds_read_b128 v[90:93], v136 offset:34816
	ds_read_b128 v[94:97], v136 offset:35840
	ds_read_b128 v[212:215], v136 offset:36864
	ds_read_b128 v[216:219], v136 offset:37888
	ds_read_b128 v[220:223], v136 offset:38912
	ds_read_b128 v[224:227], v136 offset:39936
	s_nop 0
	global_load_lds_dwordx4 v130, s[18:19]
	s_mov_b32 m0, s35
	s_nop 0
	global_load_lds_dwordx4 v132, s[18:19]
	s_waitcnt lgkmcnt(8)
	s_barrier
	s_waitcnt lgkmcnt(0)
	s_setprio 3
	s_waitcnt lgkmcnt(0)
	v_mfma_f32_16x16x32_bf16 v[2:5], v[82:85], v[114:117], v[50:53]
	v_mfma_f32_16x16x32_bf16 v[30:33], v[86:89], v[118:121], v[2:5]
	v_mfma_f32_16x16x32_bf16 v[2:5], v[82:85], v[122:125], v[54:57]
	v_mfma_f32_16x16x32_bf16 v[26:29], v[86:89], v[126:129], v[2:5]
	v_mfma_f32_16x16x32_bf16 v[2:5], v[90:93], v[114:117], v[58:61]
	v_mfma_f32_16x16x32_bf16 v[22:25], v[94:97], v[118:121], v[2:5]
	v_mfma_f32_16x16x32_bf16 v[2:5], v[90:93], v[122:125], v[62:65]
	v_mfma_f32_16x16x32_bf16 v[18:21], v[94:97], v[126:129], v[2:5]
	v_mfma_f32_16x16x32_bf16 v[2:5], v[212:215], v[114:117], v[66:69]
	v_mfma_f32_16x16x32_bf16 v[14:17], v[216:219], v[118:121], v[2:5]
	v_mfma_f32_16x16x32_bf16 v[2:5], v[212:215], v[122:125], v[70:73]
	v_mfma_f32_16x16x32_bf16 v[10:13], v[216:219], v[126:129], v[2:5]
	v_mfma_f32_16x16x32_bf16 v[2:5], v[220:223], v[114:117], v[74:77]
	v_mfma_f32_16x16x32_bf16 v[6:9], v[224:227], v[118:121], v[2:5]
	v_mfma_f32_16x16x32_bf16 v[2:5], v[220:223], v[122:125], v[78:81]
	v_mfma_f32_16x16x32_bf16 v[2:5], v[224:227], v[126:129], v[2:5]
	s_setprio 0
	s_barrier
	s_add_u32 s18, s56, 0x180
	s_addc_u32 s19, s57, 0
	s_mov_b32 m0, s36
	ds_read_b128 v[228:231], v137 offset:49152
	ds_read_b128 v[232:235], v137 offset:50176
	ds_read_b128 v[236:239], v137 offset:51200
	ds_read_b128 v[240:243], v137 offset:52224
	s_nop 0
	global_load_lds_dwordx4 v130, s[18:19]
	s_mov_b32 m0, s37
	s_nop 0
	global_load_lds_dwordx4 v132, s[18:19]
	s_barrier
	s_waitcnt lgkmcnt(0)
	s_setprio 3
	s_waitcnt lgkmcnt(0)
	v_mfma_f32_16x16x32_bf16 v[50:53], v[82:85], v[228:231], v[98:101]
	v_mfma_f32_16x16x32_bf16 v[34:37], v[90:93], v[236:239], v[34:37]
	v_mfma_f32_16x16x32_bf16 v[62:65], v[86:89], v[232:235], v[50:53]
	v_mfma_f32_16x16x32_bf16 v[42:45], v[82:85], v[236:239], v[42:45]
	v_mfma_f32_16x16x32_bf16 v[50:53], v[94:97], v[240:243], v[34:37]
	v_mfma_f32_16x16x32_bf16 v[34:37], v[212:215], v[228:231], v[38:41]
	v_mfma_f32_16x16x32_bf16 v[58:61], v[86:89], v[240:243], v[42:45]
	v_mfma_f32_16x16x32_bf16 v[42:45], v[90:93], v[228:231], v[46:49]
	v_mfma_f32_16x16x32_bf16 v[46:49], v[216:219], v[232:235], v[34:37]
	v_mfma_f32_16x16x32_bf16 v[34:37], v[212:215], v[236:239], v[102:105]
	v_mfma_f32_16x16x32_bf16 v[54:57], v[94:97], v[232:235], v[42:45]
	v_mfma_f32_16x16x32_bf16 v[42:45], v[216:219], v[240:243], v[34:37]
	v_mfma_f32_16x16x32_bf16 v[34:37], v[220:223], v[228:231], v[106:109]
	v_mfma_f32_16x16x32_bf16 v[38:41], v[224:227], v[232:235], v[34:37]
	v_mfma_f32_16x16x32_bf16 v[34:37], v[220:223], v[236:239], v[110:113]
	v_mfma_f32_16x16x32_bf16 v[34:37], v[224:227], v[240:243], v[34:37]
	s_setprio 0
	s_add_u32 s18, s17, 0x180
	s_addc_u32 s19, s58, 0
	s_mov_b32 m0, s38
	s_barrier
	ds_read_b128 v[98:101], v136 offset:49152
	ds_read_b128 v[102:105], v136 offset:50176
	ds_read_b128 v[106:109], v136 offset:51200
	ds_read_b128 v[110:113], v136 offset:52224
	ds_read_b128 v[212:215], v136 offset:53248
	ds_read_b128 v[216:219], v136 offset:54272
	ds_read_b128 v[220:223], v136 offset:55296
	ds_read_b128 v[224:227], v136 offset:56320
	s_nop 0
	global_load_lds_dwordx4 v130, s[18:19]
	s_mov_b32 m0, s39
	s_nop 0
	global_load_lds_dwordx4 v132, s[18:19]
	s_barrier
	s_waitcnt lgkmcnt(0)
	s_setprio 3
	s_waitcnt lgkmcnt(0)
	v_mfma_f32_16x16x32_bf16 v[66:69], v[98:101], v[114:117], v[142:145]
	v_mfma_f32_16x16x32_bf16 v[94:97], v[102:105], v[118:121], v[66:69]
	v_mfma_f32_16x16x32_bf16 v[66:69], v[98:101], v[122:125], v[146:149]
	v_mfma_f32_16x16x32_bf16 v[90:93], v[102:105], v[126:129], v[66:69]
	v_mfma_f32_16x16x32_bf16 v[66:69], v[106:109], v[114:117], v[150:153]
	v_mfma_f32_16x16x32_bf16 v[86:89], v[110:113], v[118:121], v[66:69]
	v_mfma_f32_16x16x32_bf16 v[66:69], v[106:109], v[122:125], v[154:157]
	v_mfma_f32_16x16x32_bf16 v[82:85], v[110:113], v[126:129], v[66:69]
	v_mfma_f32_16x16x32_bf16 v[66:69], v[212:215], v[114:117], v[158:161]
	v_mfma_f32_16x16x32_bf16 v[78:81], v[216:219], v[118:121], v[66:69]
	v_mfma_f32_16x16x32_bf16 v[66:69], v[212:215], v[122:125], v[162:165]
	v_mfma_f32_16x16x32_bf16 v[74:77], v[216:219], v[126:129], v[66:69]
	v_mfma_f32_16x16x32_bf16 v[66:69], v[220:223], v[114:117], v[166:169]
	v_mfma_f32_16x16x32_bf16 v[70:73], v[224:227], v[118:121], v[66:69]
	v_mfma_f32_16x16x32_bf16 v[66:69], v[220:223], v[122:125], v[170:173]
	v_mfma_f32_16x16x32_bf16 v[66:69], v[224:227], v[126:129], v[66:69]
	s_setprio 0
	s_barrier
	s_add_u32 s18, s59, 0x180
	s_addc_u32 s19, s60, 0
	s_mov_b32 m0, s40
	s_nop 0
	global_load_lds_dwordx4 v130, s[18:19]
	s_mov_b32 m0, s41
	s_nop 0
	global_load_lds_dwordx4 v132, s[18:19]
	s_waitcnt vmcnt(6)
	s_barrier
	s_setprio 3
	v_mfma_f32_16x16x32_bf16 v[114:117], v[98:101], v[228:231], v[174:177]
	v_mfma_f32_16x16x32_bf16 v[98:101], v[98:101], v[236:239], v[178:181]
	v_mfma_f32_16x16x32_bf16 v[122:125], v[102:105], v[240:243], v[98:101]
	v_mfma_f32_16x16x32_bf16 v[98:101], v[106:109], v[228:231], v[182:185]
	v_mfma_f32_16x16x32_bf16 v[118:121], v[110:113], v[232:235], v[98:101]
	v_mfma_f32_16x16x32_bf16 v[98:101], v[106:109], v[236:239], v[186:189]
	v_mfma_f32_16x16x32_bf16 v[126:129], v[102:105], v[232:235], v[114:117]
	v_mfma_f32_16x16x32_bf16 v[114:117], v[110:113], v[240:243], v[98:101]
	v_mfma_f32_16x16x32_bf16 v[98:101], v[212:215], v[228:231], v[190:193]
	v_mfma_f32_16x16x32_bf16 v[110:113], v[216:219], v[232:235], v[98:101]
	v_mfma_f32_16x16x32_bf16 v[98:101], v[212:215], v[236:239], v[194:197]
	v_mfma_f32_16x16x32_bf16 v[106:109], v[216:219], v[240:243], v[98:101]
	v_mfma_f32_16x16x32_bf16 v[98:101], v[220:223], v[228:231], v[198:201]
	v_mfma_f32_16x16x32_bf16 v[102:105], v[224:227], v[232:235], v[98:101]
	v_mfma_f32_16x16x32_bf16 v[98:101], v[220:223], v[236:239], v[202:205]
	v_mfma_f32_16x16x32_bf16 v[98:101], v[224:227], v[240:243], v[98:101]
	s_setprio 0
	s_mov_b32 s61, 0
	s_mov_b64 s[18:19], 0
	s_barrier
.LBB0_364:
	ds_read_b128 v[138:141], v137
	ds_read_b128 v[142:145], v137 offset:1024
	ds_read_b128 v[146:149], v137 offset:2048
	ds_read_b128 v[150:153], v137 offset:3072
	s_add_u32 s64, s20, s18
	s_addc_u32 s65, s21, s19
	s_add_u32 s62, s64, 0x180
	s_addc_u32 s63, s65, 0
	s_mov_b32 m0, s42
	ds_read_b128 v[154:157], v136
	ds_read_b128 v[158:161], v136 offset:1024
	ds_read_b128 v[162:165], v136 offset:2048
	ds_read_b128 v[166:169], v136 offset:3072
	ds_read_b128 v[170:173], v136 offset:4096
	ds_read_b128 v[174:177], v136 offset:5120
	ds_read_b128 v[178:181], v136 offset:6144
	ds_read_b128 v[182:185], v136 offset:7168
	s_nop 0
	global_load_lds_dwordx4 v130, s[62:63]
	s_mov_b32 m0, s43
	s_nop 0
	global_load_lds_dwordx4 v132, s[62:63]
	s_waitcnt lgkmcnt(8)
	s_barrier
	s_waitcnt lgkmcnt(0)
	s_setprio 3
	s_waitcnt lgkmcnt(0)
	v_mfma_f32_16x16x32_bf16 v[30:33], v[154:157], v[138:141], v[30:33]
	v_mfma_f32_16x16x32_bf16 v[26:29], v[154:157], v[146:149], v[26:29]
	v_mfma_f32_16x16x32_bf16 v[22:25], v[162:165], v[138:141], v[22:25]
	v_mfma_f32_16x16x32_bf16 v[18:21], v[162:165], v[146:149], v[18:21]
	v_mfma_f32_16x16x32_bf16 v[14:17], v[170:173], v[138:141], v[14:17]
	v_mfma_f32_16x16x32_bf16 v[10:13], v[170:173], v[146:149], v[10:13]
	v_mfma_f32_16x16x32_bf16 v[6:9], v[178:181], v[138:141], v[6:9]
	v_mfma_f32_16x16x32_bf16 v[2:5], v[178:181], v[146:149], v[2:5]
	v_mfma_f32_16x16x32_bf16 v[30:33], v[158:161], v[142:145], v[30:33]
	v_mfma_f32_16x16x32_bf16 v[26:29], v[158:161], v[150:153], v[26:29]
	v_mfma_f32_16x16x32_bf16 v[22:25], v[166:169], v[142:145], v[22:25]
	v_mfma_f32_16x16x32_bf16 v[18:21], v[166:169], v[150:153], v[18:21]
	v_mfma_f32_16x16x32_bf16 v[14:17], v[174:177], v[142:145], v[14:17]
	v_mfma_f32_16x16x32_bf16 v[10:13], v[174:177], v[150:153], v[10:13]
	v_mfma_f32_16x16x32_bf16 v[6:9], v[182:185], v[142:145], v[6:9]
	v_mfma_f32_16x16x32_bf16 v[2:5], v[182:185], v[150:153], v[2:5]
	s_setprio 0
	s_barrier
	s_add_u32 s66, s56, s18
	s_addc_u32 s67, s57, s19
	s_add_u32 s62, s66, 0x200
	s_addc_u32 s63, s67, 0
	s_mov_b32 m0, s28
	ds_read_b128 v[186:189], v137 offset:16384
	ds_read_b128 v[190:193], v137 offset:17408
	ds_read_b128 v[194:197], v137 offset:18432
	ds_read_b128 v[198:201], v137 offset:19456
	s_nop 0
	global_load_lds_dwordx4 v130, s[62:63]
	s_mov_b32 m0, s29
	s_nop 0
	global_load_lds_dwordx4 v132, s[62:63]
	s_barrier
	s_waitcnt lgkmcnt(0)
	s_setprio 3
	s_waitcnt lgkmcnt(0)
	v_mfma_f32_16x16x32_bf16 v[62:65], v[154:157], v[186:189], v[62:65]
	v_mfma_f32_16x16x32_bf16 v[58:61], v[154:157], v[194:197], v[58:61]
	v_mfma_f32_16x16x32_bf16 v[54:57], v[162:165], v[186:189], v[54:57]
	v_mfma_f32_16x16x32_bf16 v[50:53], v[162:165], v[194:197], v[50:53]
	v_mfma_f32_16x16x32_bf16 v[46:49], v[170:173], v[186:189], v[46:49]
	v_mfma_f32_16x16x32_bf16 v[42:45], v[170:173], v[194:197], v[42:45]
	v_mfma_f32_16x16x32_bf16 v[38:41], v[178:181], v[186:189], v[38:41]
	v_mfma_f32_16x16x32_bf16 v[34:37], v[178:181], v[194:197], v[34:37]
	v_mfma_f32_16x16x32_bf16 v[62:65], v[158:161], v[190:193], v[62:65]
	v_mfma_f32_16x16x32_bf16 v[58:61], v[158:161], v[198:201], v[58:61]
	v_mfma_f32_16x16x32_bf16 v[54:57], v[166:169], v[190:193], v[54:57]
	v_mfma_f32_16x16x32_bf16 v[50:53], v[166:169], v[198:201], v[50:53]
	v_mfma_f32_16x16x32_bf16 v[46:49], v[174:177], v[190:193], v[46:49]
	v_mfma_f32_16x16x32_bf16 v[42:45], v[174:177], v[198:201], v[42:45]
	v_mfma_f32_16x16x32_bf16 v[38:41], v[182:185], v[190:193], v[38:41]
	v_mfma_f32_16x16x32_bf16 v[34:37], v[182:185], v[198:201], v[34:37]
	s_setprio 0
	s_add_u32 s68, s17, s18
	s_addc_u32 s69, s58, s19
	s_add_u32 s62, s68, 0x200
	s_addc_u32 s63, s69, 0
	s_mov_b32 m0, s27
	s_barrier
	ds_read_b128 v[154:157], v136 offset:16384
	ds_read_b128 v[158:161], v136 offset:17408
	ds_read_b128 v[162:165], v136 offset:18432
	ds_read_b128 v[166:169], v136 offset:19456
	ds_read_b128 v[170:173], v136 offset:20480
	ds_read_b128 v[174:177], v136 offset:21504
	ds_read_b128 v[178:181], v136 offset:22528
	ds_read_b128 v[182:185], v136 offset:23552
	s_nop 0
	global_load_lds_dwordx4 v130, s[62:63]
	s_mov_b32 m0, s30
	s_nop 0
	global_load_lds_dwordx4 v132, s[62:63]
	s_barrier
	s_waitcnt lgkmcnt(0)
	s_setprio 3
	s_waitcnt lgkmcnt(0)
	v_mfma_f32_16x16x32_bf16 v[94:97], v[154:157], v[138:141], v[94:97]
	v_mfma_f32_16x16x32_bf16 v[90:93], v[154:157], v[146:149], v[90:93]
	v_mfma_f32_16x16x32_bf16 v[86:89], v[162:165], v[138:141], v[86:89]
	v_mfma_f32_16x16x32_bf16 v[82:85], v[162:165], v[146:149], v[82:85]
	v_mfma_f32_16x16x32_bf16 v[78:81], v[170:173], v[138:141], v[78:81]
	v_mfma_f32_16x16x32_bf16 v[74:77], v[170:173], v[146:149], v[74:77]
	v_mfma_f32_16x16x32_bf16 v[70:73], v[178:181], v[138:141], v[70:73]
	v_mfma_f32_16x16x32_bf16 v[66:69], v[178:181], v[146:149], v[66:69]
	v_mfma_f32_16x16x32_bf16 v[94:97], v[158:161], v[142:145], v[94:97]
	v_mfma_f32_16x16x32_bf16 v[90:93], v[158:161], v[150:153], v[90:93]
	v_mfma_f32_16x16x32_bf16 v[86:89], v[166:169], v[142:145], v[86:89]
	v_mfma_f32_16x16x32_bf16 v[82:85], v[166:169], v[150:153], v[82:85]
	v_mfma_f32_16x16x32_bf16 v[78:81], v[174:177], v[142:145], v[78:81]
	v_mfma_f32_16x16x32_bf16 v[74:77], v[174:177], v[150:153], v[74:77]
	v_mfma_f32_16x16x32_bf16 v[70:73], v[182:185], v[142:145], v[70:73]
	v_mfma_f32_16x16x32_bf16 v[66:69], v[182:185], v[150:153], v[66:69]
	s_setprio 0
	s_barrier
	s_add_u32 s70, s59, s18
	s_addc_u32 s71, s60, s19
	s_add_u32 s62, s70, 0x200
	s_addc_u32 s63, s71, 0
	s_mov_b32 m0, s31
	s_nop 0
	global_load_lds_dwordx4 v130, s[62:63]
	s_mov_b32 m0, s33
	s_nop 0
	global_load_lds_dwordx4 v132, s[62:63]
	s_waitcnt vmcnt(6)
	s_barrier
	s_setprio 3
	v_mfma_f32_16x16x32_bf16 v[126:129], v[154:157], v[186:189], v[126:129]
	v_mfma_f32_16x16x32_bf16 v[122:125], v[154:157], v[194:197], v[122:125]
	v_mfma_f32_16x16x32_bf16 v[118:121], v[162:165], v[186:189], v[118:121]
	v_mfma_f32_16x16x32_bf16 v[114:117], v[162:165], v[194:197], v[114:117]
	v_mfma_f32_16x16x32_bf16 v[110:113], v[170:173], v[186:189], v[110:113]
	v_mfma_f32_16x16x32_bf16 v[106:109], v[170:173], v[194:197], v[106:109]
	v_mfma_f32_16x16x32_bf16 v[102:105], v[178:181], v[186:189], v[102:105]
	v_mfma_f32_16x16x32_bf16 v[98:101], v[178:181], v[194:197], v[98:101]
	v_mfma_f32_16x16x32_bf16 v[126:129], v[158:161], v[190:193], v[126:129]
	v_mfma_f32_16x16x32_bf16 v[122:125], v[158:161], v[198:201], v[122:125]
	v_mfma_f32_16x16x32_bf16 v[118:121], v[166:169], v[190:193], v[118:121]
	v_mfma_f32_16x16x32_bf16 v[114:117], v[166:169], v[198:201], v[114:117]
	v_mfma_f32_16x16x32_bf16 v[110:113], v[174:177], v[190:193], v[110:113]
	v_mfma_f32_16x16x32_bf16 v[106:109], v[174:177], v[198:201], v[106:109]
	v_mfma_f32_16x16x32_bf16 v[102:105], v[182:185], v[190:193], v[102:105]
	v_mfma_f32_16x16x32_bf16 v[98:101], v[182:185], v[198:201], v[98:101]
	s_setprio 0
	s_barrier
	ds_read_b128 v[138:141], v137 offset:32768
	ds_read_b128 v[142:145], v137 offset:33792
	ds_read_b128 v[146:149], v137 offset:34816
	ds_read_b128 v[150:153], v137 offset:35840
	s_add_u32 s62, s64, 0x200
	s_addc_u32 s63, s65, 0
	s_mov_b32 m0, s34
	ds_read_b128 v[154:157], v136 offset:32768
	ds_read_b128 v[158:161], v136 offset:33792
	ds_read_b128 v[162:165], v136 offset:34816
	ds_read_b128 v[166:169], v136 offset:35840
	ds_read_b128 v[170:173], v136 offset:36864
	ds_read_b128 v[174:177], v136 offset:37888
	ds_read_b128 v[178:181], v136 offset:38912
	ds_read_b128 v[182:185], v136 offset:39936
	s_nop 0
	global_load_lds_dwordx4 v130, s[62:63]
	s_mov_b32 m0, s35
	s_nop 0
	global_load_lds_dwordx4 v132, s[62:63]
	s_waitcnt lgkmcnt(8)
	s_barrier
	s_waitcnt lgkmcnt(0)
	s_setprio 3
	s_waitcnt lgkmcnt(0)
	v_mfma_f32_16x16x32_bf16 v[30:33], v[154:157], v[138:141], v[30:33]
	v_mfma_f32_16x16x32_bf16 v[26:29], v[154:157], v[146:149], v[26:29]
	v_mfma_f32_16x16x32_bf16 v[22:25], v[162:165], v[138:141], v[22:25]
	v_mfma_f32_16x16x32_bf16 v[18:21], v[162:165], v[146:149], v[18:21]
	v_mfma_f32_16x16x32_bf16 v[14:17], v[170:173], v[138:141], v[14:17]
	v_mfma_f32_16x16x32_bf16 v[10:13], v[170:173], v[146:149], v[10:13]
	v_mfma_f32_16x16x32_bf16 v[6:9], v[178:181], v[138:141], v[6:9]
	v_mfma_f32_16x16x32_bf16 v[2:5], v[178:181], v[146:149], v[2:5]
	v_mfma_f32_16x16x32_bf16 v[30:33], v[158:161], v[142:145], v[30:33]
	v_mfma_f32_16x16x32_bf16 v[26:29], v[158:161], v[150:153], v[26:29]
	v_mfma_f32_16x16x32_bf16 v[22:25], v[166:169], v[142:145], v[22:25]
	v_mfma_f32_16x16x32_bf16 v[18:21], v[166:169], v[150:153], v[18:21]
	v_mfma_f32_16x16x32_bf16 v[14:17], v[174:177], v[142:145], v[14:17]
	v_mfma_f32_16x16x32_bf16 v[10:13], v[174:177], v[150:153], v[10:13]
	v_mfma_f32_16x16x32_bf16 v[6:9], v[182:185], v[142:145], v[6:9]
	v_mfma_f32_16x16x32_bf16 v[2:5], v[182:185], v[150:153], v[2:5]
	s_setprio 0
	s_barrier
	s_add_u32 s62, s66, 0x280
	s_addc_u32 s63, s67, 0
	s_mov_b32 m0, s36
	ds_read_b128 v[186:189], v137 offset:49152
	ds_read_b128 v[190:193], v137 offset:50176
	ds_read_b128 v[194:197], v137 offset:51200
	ds_read_b128 v[198:201], v137 offset:52224
	s_nop 0
	global_load_lds_dwordx4 v130, s[62:63]
	s_mov_b32 m0, s37
	s_nop 0
	global_load_lds_dwordx4 v132, s[62:63]
	s_barrier
	s_waitcnt lgkmcnt(0)
	s_setprio 3
	s_waitcnt lgkmcnt(0)
	v_mfma_f32_16x16x32_bf16 v[62:65], v[154:157], v[186:189], v[62:65]
	v_mfma_f32_16x16x32_bf16 v[58:61], v[154:157], v[194:197], v[58:61]
	v_mfma_f32_16x16x32_bf16 v[54:57], v[162:165], v[186:189], v[54:57]
	v_mfma_f32_16x16x32_bf16 v[50:53], v[162:165], v[194:197], v[50:53]
	v_mfma_f32_16x16x32_bf16 v[46:49], v[170:173], v[186:189], v[46:49]
	v_mfma_f32_16x16x32_bf16 v[42:45], v[170:173], v[194:197], v[42:45]
	v_mfma_f32_16x16x32_bf16 v[38:41], v[178:181], v[186:189], v[38:41]
	v_mfma_f32_16x16x32_bf16 v[34:37], v[178:181], v[194:197], v[34:37]
	v_mfma_f32_16x16x32_bf16 v[62:65], v[158:161], v[190:193], v[62:65]
	v_mfma_f32_16x16x32_bf16 v[58:61], v[158:161], v[198:201], v[58:61]
	v_mfma_f32_16x16x32_bf16 v[54:57], v[166:169], v[190:193], v[54:57]
	v_mfma_f32_16x16x32_bf16 v[50:53], v[166:169], v[198:201], v[50:53]
	v_mfma_f32_16x16x32_bf16 v[46:49], v[174:177], v[190:193], v[46:49]
	v_mfma_f32_16x16x32_bf16 v[42:45], v[174:177], v[198:201], v[42:45]
	v_mfma_f32_16x16x32_bf16 v[38:41], v[182:185], v[190:193], v[38:41]
	v_mfma_f32_16x16x32_bf16 v[34:37], v[182:185], v[198:201], v[34:37]
	s_setprio 0
	s_add_u32 s62, s68, 0x280
	s_addc_u32 s63, s69, 0
	s_mov_b32 m0, s38
	s_barrier
	ds_read_b128 v[154:157], v136 offset:49152
	ds_read_b128 v[158:161], v136 offset:50176
	ds_read_b128 v[162:165], v136 offset:51200
	ds_read_b128 v[166:169], v136 offset:52224
	ds_read_b128 v[170:173], v136 offset:53248
	ds_read_b128 v[174:177], v136 offset:54272
	ds_read_b128 v[178:181], v136 offset:55296
	ds_read_b128 v[182:185], v136 offset:56320
	s_nop 0
	global_load_lds_dwordx4 v130, s[62:63]
	s_mov_b32 m0, s39
	s_nop 0
	global_load_lds_dwordx4 v132, s[62:63]
	s_barrier
	s_waitcnt lgkmcnt(0)
	s_setprio 3
	s_waitcnt lgkmcnt(0)
	v_mfma_f32_16x16x32_bf16 v[94:97], v[154:157], v[138:141], v[94:97]
	v_mfma_f32_16x16x32_bf16 v[90:93], v[154:157], v[146:149], v[90:93]
	v_mfma_f32_16x16x32_bf16 v[86:89], v[162:165], v[138:141], v[86:89]
	v_mfma_f32_16x16x32_bf16 v[82:85], v[162:165], v[146:149], v[82:85]
	v_mfma_f32_16x16x32_bf16 v[78:81], v[170:173], v[138:141], v[78:81]
	v_mfma_f32_16x16x32_bf16 v[74:77], v[170:173], v[146:149], v[74:77]
	v_mfma_f32_16x16x32_bf16 v[70:73], v[178:181], v[138:141], v[70:73]
	v_mfma_f32_16x16x32_bf16 v[66:69], v[178:181], v[146:149], v[66:69]
	v_mfma_f32_16x16x32_bf16 v[94:97], v[158:161], v[142:145], v[94:97]
	v_mfma_f32_16x16x32_bf16 v[90:93], v[158:161], v[150:153], v[90:93]
	v_mfma_f32_16x16x32_bf16 v[86:89], v[166:169], v[142:145], v[86:89]
	v_mfma_f32_16x16x32_bf16 v[82:85], v[166:169], v[150:153], v[82:85]
	v_mfma_f32_16x16x32_bf16 v[78:81], v[174:177], v[142:145], v[78:81]
	v_mfma_f32_16x16x32_bf16 v[74:77], v[174:177], v[150:153], v[74:77]
	v_mfma_f32_16x16x32_bf16 v[70:73], v[182:185], v[142:145], v[70:73]
	v_mfma_f32_16x16x32_bf16 v[66:69], v[182:185], v[150:153], v[66:69]
	s_setprio 0
	s_barrier
	s_add_u32 s62, s70, 0x280
	s_addc_u32 s63, s71, 0
	s_mov_b32 m0, s40
	s_nop 0
	global_load_lds_dwordx4 v130, s[62:63]
	s_mov_b32 m0, s41
	s_nop 0
	global_load_lds_dwordx4 v132, s[62:63]
	s_waitcnt vmcnt(6)
	s_barrier
	s_setprio 3
	v_mfma_f32_16x16x32_bf16 v[126:129], v[154:157], v[186:189], v[126:129]
	v_mfma_f32_16x16x32_bf16 v[122:125], v[154:157], v[194:197], v[122:125]
	v_mfma_f32_16x16x32_bf16 v[118:121], v[162:165], v[186:189], v[118:121]
	v_mfma_f32_16x16x32_bf16 v[114:117], v[162:165], v[194:197], v[114:117]
	v_mfma_f32_16x16x32_bf16 v[110:113], v[170:173], v[186:189], v[110:113]
	v_mfma_f32_16x16x32_bf16 v[106:109], v[170:173], v[194:197], v[106:109]
	v_mfma_f32_16x16x32_bf16 v[102:105], v[178:181], v[186:189], v[102:105]
	v_mfma_f32_16x16x32_bf16 v[98:101], v[178:181], v[194:197], v[98:101]
	v_mfma_f32_16x16x32_bf16 v[126:129], v[158:161], v[190:193], v[126:129]
	v_mfma_f32_16x16x32_bf16 v[122:125], v[158:161], v[198:201], v[122:125]
	v_mfma_f32_16x16x32_bf16 v[118:121], v[166:169], v[190:193], v[118:121]
	v_mfma_f32_16x16x32_bf16 v[114:117], v[166:169], v[198:201], v[114:117]
	v_mfma_f32_16x16x32_bf16 v[110:113], v[174:177], v[190:193], v[110:113]
	v_mfma_f32_16x16x32_bf16 v[106:109], v[174:177], v[198:201], v[106:109]
	v_mfma_f32_16x16x32_bf16 v[102:105], v[182:185], v[190:193], v[102:105]
	v_mfma_f32_16x16x32_bf16 v[98:101], v[182:185], v[198:201], v[98:101]
	s_setprio 0
	s_add_i32 s61, s61, 2
	s_add_u32 s18, s18, 0x100
	s_addc_u32 s19, s19, 0
	s_cmp_gt_u32 s61, 11
	s_barrier
	s_cbranch_scc0 .LBB0_364
	s_lshl_b64 s[14:15], s[14:15], 1
	s_add_u32 s14, s44, s14
	s_addc_u32 s15, s45, s15
	s_mov_b32 m0, s42
	ds_read_b128 v[142:145], v137
	ds_read_b128 v[146:149], v137 offset:1024
	ds_read_b128 v[150:153], v137 offset:2048
	ds_read_b128 v[154:157], v137 offset:3072
	ds_read_b128 v[158:161], v136
	ds_read_b128 v[162:165], v136 offset:1024
	ds_read_b128 v[166:169], v136 offset:2048
	ds_read_b128 v[170:173], v136 offset:3072
	ds_read_b128 v[174:177], v136 offset:4096
	ds_read_b128 v[178:181], v136 offset:5120
	ds_read_b128 v[182:185], v136 offset:6144
	ds_read_b128 v[186:189], v136 offset:7168
	s_nop 0
	global_load_lds_dwordx4 v130, s[14:15]
	s_mov_b32 m0, s43
	s_nop 0
	global_load_lds_dwordx4 v132, s[14:15]
	s_barrier
	s_waitcnt lgkmcnt(0)
	s_setprio 3
	s_waitcnt lgkmcnt(0)
	v_mfma_f32_16x16x32_bf16 v[30:33], v[158:161], v[142:145], v[30:33]
	v_mfma_f32_16x16x32_bf16 v[26:29], v[158:161], v[150:153], v[26:29]
	v_mfma_f32_16x16x32_bf16 v[22:25], v[166:169], v[142:145], v[22:25]
	v_mfma_f32_16x16x32_bf16 v[18:21], v[166:169], v[150:153], v[18:21]
	v_mfma_f32_16x16x32_bf16 v[14:17], v[174:177], v[142:145], v[14:17]
	v_mfma_f32_16x16x32_bf16 v[10:13], v[174:177], v[150:153], v[10:13]
	v_mfma_f32_16x16x32_bf16 v[6:9], v[182:185], v[142:145], v[6:9]
	v_mfma_f32_16x16x32_bf16 v[2:5], v[182:185], v[150:153], v[2:5]
	v_mfma_f32_16x16x32_bf16 v[30:33], v[162:165], v[146:149], v[30:33]
	v_mfma_f32_16x16x32_bf16 v[26:29], v[162:165], v[154:157], v[26:29]
	v_mfma_f32_16x16x32_bf16 v[22:25], v[170:173], v[146:149], v[22:25]
	v_mfma_f32_16x16x32_bf16 v[18:21], v[170:173], v[154:157], v[18:21]
	v_mfma_f32_16x16x32_bf16 v[14:17], v[178:181], v[146:149], v[14:17]
	v_mfma_f32_16x16x32_bf16 v[10:13], v[178:181], v[154:157], v[10:13]
	v_mfma_f32_16x16x32_bf16 v[6:9], v[186:189], v[146:149], v[6:9]
	v_mfma_f32_16x16x32_bf16 v[2:5], v[186:189], v[154:157], v[2:5]
	s_setprio 0
	s_barrier
	ds_read_b128 v[190:193], v137 offset:16384
	ds_read_b128 v[194:197], v137 offset:17408
	ds_read_b128 v[198:201], v137 offset:18432
	ds_read_b128 v[202:205], v137 offset:19456
	s_barrier
	s_waitcnt lgkmcnt(0)
	s_setprio 3
	s_waitcnt lgkmcnt(0)
	v_mfma_f32_16x16x32_bf16 v[62:65], v[158:161], v[190:193], v[62:65]
	v_mfma_f32_16x16x32_bf16 v[58:61], v[158:161], v[198:201], v[58:61]
	v_mfma_f32_16x16x32_bf16 v[54:57], v[166:169], v[190:193], v[54:57]
	v_mfma_f32_16x16x32_bf16 v[50:53], v[166:169], v[198:201], v[50:53]
	v_mfma_f32_16x16x32_bf16 v[46:49], v[174:177], v[190:193], v[46:49]
	v_mfma_f32_16x16x32_bf16 v[42:45], v[174:177], v[198:201], v[42:45]
	v_mfma_f32_16x16x32_bf16 v[38:41], v[182:185], v[190:193], v[38:41]
	v_mfma_f32_16x16x32_bf16 v[34:37], v[182:185], v[198:201], v[34:37]
	v_mfma_f32_16x16x32_bf16 v[62:65], v[162:165], v[194:197], v[62:65]
	v_mfma_f32_16x16x32_bf16 v[58:61], v[162:165], v[202:205], v[58:61]
	v_mfma_f32_16x16x32_bf16 v[54:57], v[170:173], v[194:197], v[54:57]
	v_mfma_f32_16x16x32_bf16 v[50:53], v[170:173], v[202:205], v[50:53]
	v_mfma_f32_16x16x32_bf16 v[46:49], v[178:181], v[194:197], v[46:49]
	v_mfma_f32_16x16x32_bf16 v[42:45], v[178:181], v[202:205], v[42:45]
	v_mfma_f32_16x16x32_bf16 v[38:41], v[186:189], v[194:197], v[38:41]
	v_mfma_f32_16x16x32_bf16 v[34:37], v[186:189], v[202:205], v[34:37]
	s_setprio 0
	s_barrier
	ds_read_b128 v[158:161], v136 offset:16384
	ds_read_b128 v[162:165], v136 offset:17408
	ds_read_b128 v[166:169], v136 offset:18432
	ds_read_b128 v[170:173], v136 offset:19456
	ds_read_b128 v[174:177], v136 offset:20480
	ds_read_b128 v[178:181], v136 offset:21504
	ds_read_b128 v[182:185], v136 offset:22528
	ds_read_b128 v[186:189], v136 offset:23552
	s_waitcnt vmcnt(4)
	s_barrier
	s_waitcnt lgkmcnt(0)
	s_setprio 3
	s_waitcnt lgkmcnt(0)
	v_mfma_f32_16x16x32_bf16 v[94:97], v[158:161], v[142:145], v[94:97]
	v_mfma_f32_16x16x32_bf16 v[90:93], v[158:161], v[150:153], v[90:93]
	v_mfma_f32_16x16x32_bf16 v[86:89], v[166:169], v[142:145], v[86:89]
	v_mfma_f32_16x16x32_bf16 v[82:85], v[166:169], v[150:153], v[82:85]
	v_mfma_f32_16x16x32_bf16 v[78:81], v[174:177], v[142:145], v[78:81]
	v_mfma_f32_16x16x32_bf16 v[74:77], v[174:177], v[150:153], v[74:77]
	v_mfma_f32_16x16x32_bf16 v[70:73], v[182:185], v[142:145], v[70:73]
	v_mfma_f32_16x16x32_bf16 v[66:69], v[182:185], v[150:153], v[66:69]
	v_mfma_f32_16x16x32_bf16 v[212:215], v[162:165], v[146:149], v[94:97]
	v_mfma_f32_16x16x32_bf16 v[216:219], v[162:165], v[154:157], v[90:93]
	v_mfma_f32_16x16x32_bf16 v[220:223], v[170:173], v[146:149], v[86:89]
	v_mfma_f32_16x16x32_bf16 v[224:227], v[170:173], v[154:157], v[82:85]
	v_mfma_f32_16x16x32_bf16 v[228:231], v[178:181], v[146:149], v[78:81]
	v_mfma_f32_16x16x32_bf16 v[232:235], v[178:181], v[154:157], v[74:77]
	v_mfma_f32_16x16x32_bf16 v[142:145], v[186:189], v[146:149], v[70:73]
	v_mfma_f32_16x16x32_bf16 v[146:149], v[186:189], v[154:157], v[66:69]
	s_setprio 0
	s_setprio 3
	v_mfma_f32_16x16x32_bf16 v[66:69], v[158:161], v[190:193], v[126:129]
	v_mfma_f32_16x16x32_bf16 v[150:153], v[162:165], v[194:197], v[66:69]
	v_mfma_f32_16x16x32_bf16 v[66:69], v[158:161], v[198:201], v[122:125]
	v_mfma_f32_16x16x32_bf16 v[154:157], v[162:165], v[202:205], v[66:69]
	v_mfma_f32_16x16x32_bf16 v[66:69], v[166:169], v[190:193], v[118:121]
	v_mfma_f32_16x16x32_bf16 v[158:161], v[170:173], v[194:197], v[66:69]
	v_mfma_f32_16x16x32_bf16 v[66:69], v[166:169], v[198:201], v[114:117]
	v_mfma_f32_16x16x32_bf16 v[162:165], v[170:173], v[202:205], v[66:69]
	v_mfma_f32_16x16x32_bf16 v[66:69], v[174:177], v[190:193], v[110:113]
	v_mfma_f32_16x16x32_bf16 v[166:169], v[178:181], v[194:197], v[66:69]
	v_mfma_f32_16x16x32_bf16 v[66:69], v[174:177], v[198:201], v[106:109]
	v_mfma_f32_16x16x32_bf16 v[170:173], v[178:181], v[202:205], v[66:69]
	v_mfma_f32_16x16x32_bf16 v[66:69], v[182:185], v[190:193], v[102:105]
	v_mfma_f32_16x16x32_bf16 v[174:177], v[186:189], v[194:197], v[66:69]
	v_mfma_f32_16x16x32_bf16 v[66:69], v[182:185], v[198:201], v[98:101]
	v_mfma_f32_16x16x32_bf16 v[178:181], v[186:189], v[202:205], v[66:69]
	s_setprio 0
	s_barrier
	ds_read_b128 v[182:185], v137 offset:32768
	ds_read_b128 v[186:189], v137 offset:33792
	ds_read_b128 v[190:193], v137 offset:34816
	ds_read_b128 v[194:197], v137 offset:35840
	s_nop 0
	ds_read_b128 v[66:69], v136 offset:32768
	ds_read_b128 v[70:73], v136 offset:33792
	ds_read_b128 v[82:85], v136 offset:34816
	ds_read_b128 v[86:89], v136 offset:35840
	ds_read_b128 v[198:201], v136 offset:36864
	ds_read_b128 v[202:205], v136 offset:37888
	ds_read_b128 v[236:239], v136 offset:38912
	ds_read_b128 v[240:243], v136 offset:39936
	s_waitcnt vmcnt(2)
	s_barrier
	s_waitcnt lgkmcnt(0)
	s_setprio 3
	s_waitcnt lgkmcnt(0)
	v_mfma_f32_16x16x32_bf16 v[30:33], v[66:69], v[182:185], v[30:33]
	v_mfma_f32_16x16x32_bf16 v[26:29], v[66:69], v[190:193], v[26:29]
	v_mfma_f32_16x16x32_bf16 v[22:25], v[82:85], v[182:185], v[22:25]
	v_mfma_f32_16x16x32_bf16 v[18:21], v[82:85], v[190:193], v[18:21]
	v_mfma_f32_16x16x32_bf16 v[14:17], v[198:201], v[182:185], v[14:17]
	v_mfma_f32_16x16x32_bf16 v[10:13], v[198:201], v[190:193], v[10:13]
	v_mfma_f32_16x16x32_bf16 v[6:9], v[236:239], v[182:185], v[6:9]
	v_mfma_f32_16x16x32_bf16 v[2:5], v[236:239], v[190:193], v[2:5]
	v_mfma_f32_16x16x32_bf16 v[122:125], v[70:73], v[186:189], v[30:33]
	v_mfma_f32_16x16x32_bf16 v[126:129], v[70:73], v[194:197], v[26:29]
	v_mfma_f32_16x16x32_bf16 v[106:109], v[86:89], v[186:189], v[22:25]
	v_mfma_f32_16x16x32_bf16 v[110:113], v[86:89], v[194:197], v[18:21]
	v_mfma_f32_16x16x32_bf16 v[90:93], v[202:205], v[186:189], v[14:17]
	v_mfma_f32_16x16x32_bf16 v[94:97], v[202:205], v[194:197], v[10:13]
	v_mfma_f32_16x16x32_bf16 v[74:77], v[240:243], v[186:189], v[6:9]
	v_mfma_f32_16x16x32_bf16 v[78:81], v[240:243], v[194:197], v[2:5]
	s_setprio 0
	s_barrier
	s_nop 0
	ds_read_b128 v[2:5], v137 offset:49152
	ds_read_b128 v[6:9], v137 offset:50176
	ds_read_b128 v[244:247], v137 offset:51200
	ds_read_b128 v[248:251], v137 offset:52224
	s_waitcnt vmcnt(0)
	s_barrier
	s_waitcnt lgkmcnt(0)
	s_setprio 3
	s_waitcnt lgkmcnt(0)
	v_mfma_f32_16x16x32_bf16 v[10:13], v[66:69], v[2:5], v[62:65]
	v_mfma_f32_16x16x32_bf16 v[114:117], v[70:73], v[6:9], v[10:13]
	v_mfma_f32_16x16x32_bf16 v[10:13], v[66:69], v[244:247], v[58:61]
	v_mfma_f32_16x16x32_bf16 v[118:121], v[70:73], v[248:251], v[10:13]
	v_mfma_f32_16x16x32_bf16 v[10:13], v[82:85], v[2:5], v[54:57]
	v_mfma_f32_16x16x32_bf16 v[98:101], v[86:89], v[6:9], v[10:13]
	v_mfma_f32_16x16x32_bf16 v[10:13], v[82:85], v[244:247], v[50:53]
	v_mfma_f32_16x16x32_bf16 v[102:105], v[86:89], v[248:251], v[10:13]
	v_mfma_f32_16x16x32_bf16 v[10:13], v[198:201], v[2:5], v[46:49]
	v_mfma_f32_16x16x32_bf16 v[82:85], v[202:205], v[6:9], v[10:13]
	v_mfma_f32_16x16x32_bf16 v[10:13], v[198:201], v[244:247], v[42:45]
	v_mfma_f32_16x16x32_bf16 v[86:89], v[202:205], v[248:251], v[10:13]
	v_mfma_f32_16x16x32_bf16 v[10:13], v[236:239], v[2:5], v[38:41]
	v_mfma_f32_16x16x32_bf16 v[66:69], v[240:243], v[6:9], v[10:13]
	v_mfma_f32_16x16x32_bf16 v[10:13], v[236:239], v[244:247], v[34:37]
	v_mfma_f32_16x16x32_bf16 v[70:73], v[240:243], v[248:251], v[10:13]
	s_setprio 0
	s_barrier
	ds_read_b128 v[18:21], v136 offset:49152
	ds_read_b128 v[22:25], v136 offset:50176
	ds_read_b128 v[38:41], v136 offset:51200
	ds_read_b128 v[198:201], v136 offset:52224
	ds_read_b128 v[202:205], v136 offset:53248
	ds_read_b128 v[236:239], v136 offset:54272
	ds_read_b128 v[240:243], v136 offset:55296
	ds_read_b128 v[138:141], v136 offset:56320
	s_barrier
	s_waitcnt lgkmcnt(0)
	s_setprio 3
	s_waitcnt lgkmcnt(0)
	v_mfma_f32_16x16x32_bf16 v[10:13], v[18:21], v[182:185], v[212:215]
	v_mfma_f32_16x16x32_bf16 v[58:61], v[22:25], v[186:189], v[10:13]
	v_mfma_f32_16x16x32_bf16 v[10:13], v[18:21], v[190:193], v[216:219]
	v_mfma_f32_16x16x32_bf16 v[62:65], v[22:25], v[194:197], v[10:13]
	v_mfma_f32_16x16x32_bf16 v[10:13], v[38:41], v[182:185], v[220:223]
	v_mfma_f32_16x16x32_bf16 v[42:45], v[198:201], v[186:189], v[10:13]
	v_mfma_f32_16x16x32_bf16 v[10:13], v[38:41], v[190:193], v[224:227]
	v_mfma_f32_16x16x32_bf16 v[46:49], v[198:201], v[194:197], v[10:13]
	v_mfma_f32_16x16x32_bf16 v[10:13], v[202:205], v[182:185], v[228:231]
	v_mfma_f32_16x16x32_bf16 v[26:29], v[236:239], v[186:189], v[10:13]
	v_mfma_f32_16x16x32_bf16 v[10:13], v[202:205], v[190:193], v[232:235]
	v_mfma_f32_16x16x32_bf16 v[30:33], v[236:239], v[194:197], v[10:13]
	v_mfma_f32_16x16x32_bf16 v[10:13], v[240:243], v[182:185], v[142:145]
	v_mfma_f32_16x16x32_bf16 v[14:17], v[240:243], v[190:193], v[146:149]
	v_mfma_f32_16x16x32_bf16 v[10:13], v[138:141], v[186:189], v[10:13]
	v_mfma_f32_16x16x32_bf16 v[14:17], v[138:141], v[194:197], v[14:17]
	s_setprio 0
	s_setprio 3
	v_mfma_f32_16x16x32_bf16 v[34:37], v[18:21], v[2:5], v[150:153]
	v_mfma_f32_16x16x32_bf16 v[18:21], v[18:21], v[244:247], v[154:157]
	v_mfma_f32_16x16x32_bf16 v[54:57], v[22:25], v[248:251], v[18:21]
	v_mfma_f32_16x16x32_bf16 v[18:21], v[38:41], v[2:5], v[158:161]
	v_mfma_f32_16x16x32_bf16 v[50:53], v[22:25], v[6:9], v[34:37]
	v_mfma_f32_16x16x32_bf16 v[34:37], v[198:201], v[6:9], v[18:21]
	v_mfma_f32_16x16x32_bf16 v[18:21], v[38:41], v[244:247], v[162:165]
	v_mfma_f32_16x16x32_bf16 v[38:41], v[198:201], v[248:251], v[18:21]
	v_mfma_f32_16x16x32_bf16 v[18:21], v[202:205], v[2:5], v[166:169]
	v_mfma_f32_16x16x32_bf16 v[2:5], v[240:243], v[2:5], v[174:177]
	v_mfma_f32_16x16x32_bf16 v[18:21], v[236:239], v[6:9], v[18:21]
	v_mfma_f32_16x16x32_bf16 v[22:25], v[202:205], v[244:247], v[170:173]
	v_mfma_f32_16x16x32_bf16 v[2:5], v[138:141], v[6:9], v[2:5]
	v_mfma_f32_16x16x32_bf16 v[6:9], v[240:243], v[244:247], v[178:181]
	v_mfma_f32_16x16x32_bf16 v[22:25], v[236:239], v[248:251], v[22:25]
	v_mfma_f32_16x16x32_bf16 v[6:9], v[138:141], v[248:251], v[6:9]
	s_setprio 0
	s_and_b64 vcc, exec, s[10:11]
	s_barrier
	s_cbranch_vccz .LBB0_367
	s_barrier

.LBB0_400:
	s_ashr_i32 s18, s43, 31
	s_lshr_b32 s18, s18, 27
	s_add_i32 s19, s43, s18
	s_and_b32 s18, s19, 0xffffffe0
	s_sub_i32 s18, s43, s18
	s_lshl_b32 s19, s19, 6
	s_lshl_b32 s20, s43, 8
	s_ashr_i32 s18, s18, 3
	s_and_b32 s19, s19, 0xfffff800
	s_and_b32 s20, s20, 0x700
	s_or_b32 s19, s19, s20
	s_lshl_b32 s20, s18, 8
	s_mul_hi_i32 s23, s20, s34
	s_mul_i32 s22, s20, s34
	s_lshl_b64 s[22:23], s[22:23], 1
	s_add_u32 s22, s6, s22
	s_addc_u32 s23, s7, s23
	s_mov_b64 s[24:25], s[22:23]
	s_add_i32 s44, s42, 0x10000
	s_mov_b32 m0, s44
	global_load_lds_dwordx4 v132, s[24:25]
	v_lshl_add_u64 v[2:3], s[24:25], 0, v[130:131]
	s_mul_hi_i32 s25, s19, s34
	s_mul_i32 s24, s19, s34
	s_add_i32 s45, s42, 0x12000
	s_lshl_b64 s[24:25], s[24:25], 1
	s_add_u32 s24, s2, s24
	s_addc_u32 s25, s3, s25
	s_mov_b32 m0, s45
	s_mov_b64 s[26:27], s[24:25]
	global_load_lds_dwordx4 v[2:3], off
	s_mov_b32 m0, s42
	v_lshl_add_u64 v[2:3], s[26:27], 0, v[132:133]
	s_or_b32 s21, s20, 0x80
	global_load_lds_dwordx4 v[2:3], off
	v_lshl_add_u64 v[2:3], s[26:27], 0, v[130:131]
	s_mul_hi_i32 s27, s21, s34
	s_mul_i32 s26, s21, s34
	s_add_i32 s46, s42, 0x2000
	s_lshl_b64 s[26:27], s[26:27], 1
	s_add_u32 s26, s6, s26
	s_addc_u32 s27, s7, s27
	s_mov_b32 m0, s46
	s_mov_b64 s[28:29], s[26:27]
	s_add_i32 s47, s42, 0x14000
	global_load_lds_dwordx4 v[2:3], off
	s_mov_b32 m0, s47
	v_lshl_add_u64 v[2:3], s[28:29], 0, v[132:133]
	s_or_b32 s21, s19, 0x80
	global_load_lds_dwordx4 v[2:3], off
	v_lshl_add_u64 v[2:3], s[28:29], 0, v[130:131]
	s_mul_hi_i32 s29, s21, s34
	s_mul_i32 s28, s21, s34
	s_add_i32 s48, s42, 0x16000
	s_lshl_b64 s[28:29], s[28:29], 1
	s_add_u32 s28, s2, s28
	s_addc_u32 s29, s3, s29
	s_mov_b32 m0, s48
	s_mov_b64 s[30:31], s[28:29]
	s_add_i32 s49, s42, 0x4000
	global_load_lds_dwordx4 v[2:3], off
	s_mov_b32 m0, s49
	v_lshl_add_u64 v[2:3], s[30:31], 0, v[132:133]
	s_add_i32 s50, s42, 0x6000
	global_load_lds_dwordx4 v[2:3], off
	v_lshl_add_u64 v[2:3], s[30:31], 0, v[130:131]
	s_mov_b32 m0, s50
	s_andn2_b64 vcc, exec, s[12:13]
	global_load_lds_dwordx4 v[2:3], off
	s_cbranch_vccnz .LBB0_402
	s_barrier

.LBB0_403:
	ds_read_b128 v[134:137], v217
	ds_read_b128 v[138:141], v217 offset:1024
	ds_read_b128 v[142:145], v217 offset:2048
	ds_read_b128 v[146:149], v217 offset:3072
	s_add_u32 s62, s28, s30
	s_addc_u32 s63, s29, s31
	s_add_u32 s60, s62, 0x80
	s_addc_u32 s61, s63, 0
	s_add_i32 s59, s42, 0xc000
	ds_read_b128 v[150:153], v216
	ds_read_b128 v[154:157], v216 offset:1024
	ds_read_b128 v[158:161], v216 offset:2048
	ds_read_b128 v[162:165], v216 offset:3072
	ds_read_b128 v[166:169], v216 offset:4096
	ds_read_b128 v[170:173], v216 offset:5120
	ds_read_b128 v[174:177], v216 offset:6144
	ds_read_b128 v[178:181], v216 offset:7168
	s_mov_b32 m0, s59
	v_lshl_add_u64 v[182:183], s[60:61], 0, v[132:133]
	s_add_i32 s58, s42, 0xe000
	global_load_lds_dwordx4 v[182:183], off
	s_mov_b32 m0, s58
	s_nop 0
	global_load_lds_dwordx4 v130, s[60:61]
	s_waitcnt lgkmcnt(8)
	s_barrier
	s_waitcnt lgkmcnt(0)
	s_setprio 3
	s_waitcnt lgkmcnt(0)
	v_mfma_f32_16x16x32_bf16 v[2:5], v[150:153], v[134:137], v[2:5]
	v_mfma_f32_16x16x32_bf16 v[6:9], v[150:153], v[142:145], v[6:9]
	v_mfma_f32_16x16x32_bf16 v[10:13], v[158:161], v[134:137], v[10:13]
	v_mfma_f32_16x16x32_bf16 v[22:25], v[158:161], v[142:145], v[22:25]
	v_mfma_f32_16x16x32_bf16 v[34:37], v[166:169], v[134:137], v[34:37]
	v_mfma_f32_16x16x32_bf16 v[46:49], v[166:169], v[142:145], v[46:49]
	v_mfma_f32_16x16x32_bf16 v[58:61], v[174:177], v[134:137], v[58:61]
	v_mfma_f32_16x16x32_bf16 v[70:73], v[174:177], v[142:145], v[70:73]
	v_mfma_f32_16x16x32_bf16 v[2:5], v[154:157], v[138:141], v[2:5]
	v_mfma_f32_16x16x32_bf16 v[6:9], v[154:157], v[146:149], v[6:9]
	v_mfma_f32_16x16x32_bf16 v[10:13], v[162:165], v[138:141], v[10:13]
	v_mfma_f32_16x16x32_bf16 v[22:25], v[162:165], v[146:149], v[22:25]
	v_mfma_f32_16x16x32_bf16 v[34:37], v[170:173], v[138:141], v[34:37]
	v_mfma_f32_16x16x32_bf16 v[46:49], v[170:173], v[146:149], v[46:49]
	v_mfma_f32_16x16x32_bf16 v[58:61], v[178:181], v[138:141], v[58:61]
	v_mfma_f32_16x16x32_bf16 v[70:73], v[178:181], v[146:149], v[70:73]
	s_setprio 0
	s_barrier
	s_add_i32 s57, s57, 2
	s_add_u32 s64, s22, s30
	s_addc_u32 s65, s23, s31
	s_add_u32 s60, s64, 0x100
	s_addc_u32 s61, s65, 0
	s_mov_b32 m0, s44
	ds_read_b128 v[182:185], v217 offset:16384
	ds_read_b128 v[186:189], v217 offset:17408
	ds_read_b128 v[190:193], v217 offset:18432
	ds_read_b128 v[194:197], v217 offset:19456
	s_nop 0
	global_load_lds_dwordx4 v132, s[60:61]
	s_mov_b32 m0, s45
	s_nop 0
	global_load_lds_dwordx4 v130, s[60:61]
	s_barrier
	s_waitcnt lgkmcnt(0)
	s_setprio 3
	s_waitcnt lgkmcnt(0)
	v_mfma_f32_16x16x32_bf16 v[14:17], v[150:153], v[182:185], v[14:17]
	v_mfma_f32_16x16x32_bf16 v[26:29], v[150:153], v[190:193], v[26:29]
	v_mfma_f32_16x16x32_bf16 v[38:41], v[158:161], v[182:185], v[38:41]
	v_mfma_f32_16x16x32_bf16 v[50:53], v[158:161], v[190:193], v[50:53]
	v_mfma_f32_16x16x32_bf16 v[62:65], v[166:169], v[182:185], v[62:65]
	v_mfma_f32_16x16x32_bf16 v[74:77], v[166:169], v[190:193], v[74:77]
	v_mfma_f32_16x16x32_bf16 v[82:85], v[174:177], v[182:185], v[82:85]
	v_mfma_f32_16x16x32_bf16 v[94:97], v[174:177], v[190:193], v[94:97]
	v_mfma_f32_16x16x32_bf16 v[14:17], v[154:157], v[186:189], v[14:17]
	v_mfma_f32_16x16x32_bf16 v[26:29], v[154:157], v[194:197], v[26:29]
	v_mfma_f32_16x16x32_bf16 v[38:41], v[162:165], v[186:189], v[38:41]
	v_mfma_f32_16x16x32_bf16 v[50:53], v[162:165], v[194:197], v[50:53]
	v_mfma_f32_16x16x32_bf16 v[62:65], v[170:173], v[186:189], v[62:65]
	v_mfma_f32_16x16x32_bf16 v[74:77], v[170:173], v[194:197], v[74:77]
	v_mfma_f32_16x16x32_bf16 v[82:85], v[178:181], v[186:189], v[82:85]
	v_mfma_f32_16x16x32_bf16 v[94:97], v[178:181], v[194:197], v[94:97]
	s_setprio 0
	s_add_u32 s66, s24, s30
	s_addc_u32 s67, s25, s31
	s_add_u32 s60, s66, 0x100
	s_addc_u32 s61, s67, 0
	s_mov_b32 m0, s42
	s_barrier
	ds_read_b128 v[150:153], v216 offset:16384
	ds_read_b128 v[154:157], v216 offset:17408
	ds_read_b128 v[158:161], v216 offset:18432
	ds_read_b128 v[162:165], v216 offset:19456
	ds_read_b128 v[166:169], v216 offset:20480
	ds_read_b128 v[170:173], v216 offset:21504
	ds_read_b128 v[174:177], v216 offset:22528
	ds_read_b128 v[178:181], v216 offset:23552
	s_nop 0
	global_load_lds_dwordx4 v132, s[60:61]
	s_mov_b32 m0, s46
	s_nop 0
	global_load_lds_dwordx4 v130, s[60:61]
	s_barrier
	s_waitcnt lgkmcnt(0)
	s_setprio 3
	s_waitcnt lgkmcnt(0)
	v_mfma_f32_16x16x32_bf16 v[18:21], v[150:153], v[134:137], v[18:21]
	v_mfma_f32_16x16x32_bf16 v[30:33], v[150:153], v[142:145], v[30:33]
	v_mfma_f32_16x16x32_bf16 v[42:45], v[158:161], v[134:137], v[42:45]
	v_mfma_f32_16x16x32_bf16 v[54:57], v[158:161], v[142:145], v[54:57]
	v_mfma_f32_16x16x32_bf16 v[66:69], v[166:169], v[134:137], v[66:69]
	v_mfma_f32_16x16x32_bf16 v[78:81], v[166:169], v[142:145], v[78:81]
	v_mfma_f32_16x16x32_bf16 v[86:89], v[174:177], v[134:137], v[86:89]
	v_mfma_f32_16x16x32_bf16 v[98:101], v[174:177], v[142:145], v[98:101]
	v_mfma_f32_16x16x32_bf16 v[18:21], v[154:157], v[138:141], v[18:21]
	v_mfma_f32_16x16x32_bf16 v[30:33], v[154:157], v[146:149], v[30:33]
	v_mfma_f32_16x16x32_bf16 v[42:45], v[162:165], v[138:141], v[42:45]
	v_mfma_f32_16x16x32_bf16 v[54:57], v[162:165], v[146:149], v[54:57]
	v_mfma_f32_16x16x32_bf16 v[66:69], v[170:173], v[138:141], v[66:69]
	v_mfma_f32_16x16x32_bf16 v[78:81], v[170:173], v[146:149], v[78:81]
	v_mfma_f32_16x16x32_bf16 v[86:89], v[178:181], v[138:141], v[86:89]
	v_mfma_f32_16x16x32_bf16 v[98:101], v[178:181], v[146:149], v[98:101]
	s_setprio 0
	s_barrier
	s_add_u32 s68, s26, s30
	s_addc_u32 s69, s27, s31
	s_add_u32 s60, s68, 0x100
	s_addc_u32 s61, s69, 0
	s_mov_b32 m0, s47
	s_nop 0
	global_load_lds_dwordx4 v132, s[60:61]
	s_mov_b32 m0, s48
	s_nop 0
	global_load_lds_dwordx4 v130, s[60:61]
	s_waitcnt vmcnt(6)
	s_barrier
	s_setprio 3
	v_mfma_f32_16x16x32_bf16 v[90:93], v[150:153], v[182:185], v[90:93]
	v_mfma_f32_16x16x32_bf16 v[102:105], v[150:153], v[190:193], v[102:105]
	v_mfma_f32_16x16x32_bf16 v[106:109], v[158:161], v[182:185], v[106:109]
	v_mfma_f32_16x16x32_bf16 v[110:113], v[158:161], v[190:193], v[110:113]
	v_mfma_f32_16x16x32_bf16 v[114:117], v[166:169], v[182:185], v[114:117]
	v_mfma_f32_16x16x32_bf16 v[118:121], v[166:169], v[190:193], v[118:121]
	v_mfma_f32_16x16x32_bf16 v[122:125], v[174:177], v[182:185], v[122:125]
	v_mfma_f32_16x16x32_bf16 v[126:129], v[174:177], v[190:193], v[126:129]
	v_mfma_f32_16x16x32_bf16 v[90:93], v[154:157], v[186:189], v[90:93]
	v_mfma_f32_16x16x32_bf16 v[102:105], v[154:157], v[194:197], v[102:105]
	v_mfma_f32_16x16x32_bf16 v[106:109], v[162:165], v[186:189], v[106:109]
	v_mfma_f32_16x16x32_bf16 v[110:113], v[162:165], v[194:197], v[110:113]
	v_mfma_f32_16x16x32_bf16 v[114:117], v[170:173], v[186:189], v[114:117]
	v_mfma_f32_16x16x32_bf16 v[118:121], v[170:173], v[194:197], v[118:121]
	v_mfma_f32_16x16x32_bf16 v[122:125], v[178:181], v[186:189], v[122:125]
	v_mfma_f32_16x16x32_bf16 v[126:129], v[178:181], v[194:197], v[126:129]
	s_setprio 0
	s_barrier
	ds_read_b128 v[134:137], v217 offset:32768
	ds_read_b128 v[138:141], v217 offset:33792
	ds_read_b128 v[142:145], v217 offset:34816
	ds_read_b128 v[146:149], v217 offset:35840
	s_add_u32 s60, s62, 0x100
	s_addc_u32 s61, s63, 0
	s_mov_b32 m0, s49
	ds_read_b128 v[150:153], v216 offset:32768
	ds_read_b128 v[154:157], v216 offset:33792
	ds_read_b128 v[158:161], v216 offset:34816
	ds_read_b128 v[162:165], v216 offset:35840
	ds_read_b128 v[166:169], v216 offset:36864
	ds_read_b128 v[170:173], v216 offset:37888
	ds_read_b128 v[174:177], v216 offset:38912
	ds_read_b128 v[178:181], v216 offset:39936
	s_nop 0
	global_load_lds_dwordx4 v132, s[60:61]
	s_mov_b32 m0, s50
	s_nop 0
	global_load_lds_dwordx4 v130, s[60:61]
	s_waitcnt lgkmcnt(8)
	s_barrier
	s_waitcnt lgkmcnt(0)
	s_setprio 3
	s_waitcnt lgkmcnt(0)
	v_mfma_f32_16x16x32_bf16 v[2:5], v[150:153], v[134:137], v[2:5]
	v_mfma_f32_16x16x32_bf16 v[6:9], v[150:153], v[142:145], v[6:9]
	v_mfma_f32_16x16x32_bf16 v[10:13], v[158:161], v[134:137], v[10:13]
	v_mfma_f32_16x16x32_bf16 v[22:25], v[158:161], v[142:145], v[22:25]
	v_mfma_f32_16x16x32_bf16 v[34:37], v[166:169], v[134:137], v[34:37]
	v_mfma_f32_16x16x32_bf16 v[46:49], v[166:169], v[142:145], v[46:49]
	v_mfma_f32_16x16x32_bf16 v[58:61], v[174:177], v[134:137], v[58:61]
	v_mfma_f32_16x16x32_bf16 v[70:73], v[174:177], v[142:145], v[70:73]
	v_mfma_f32_16x16x32_bf16 v[2:5], v[154:157], v[138:141], v[2:5]
	v_mfma_f32_16x16x32_bf16 v[6:9], v[154:157], v[146:149], v[6:9]
	v_mfma_f32_16x16x32_bf16 v[10:13], v[162:165], v[138:141], v[10:13]
	v_mfma_f32_16x16x32_bf16 v[22:25], v[162:165], v[146:149], v[22:25]
	v_mfma_f32_16x16x32_bf16 v[34:37], v[170:173], v[138:141], v[34:37]
	v_mfma_f32_16x16x32_bf16 v[46:49], v[170:173], v[146:149], v[46:49]
	v_mfma_f32_16x16x32_bf16 v[58:61], v[178:181], v[138:141], v[58:61]
	v_mfma_f32_16x16x32_bf16 v[70:73], v[178:181], v[146:149], v[70:73]
	s_setprio 0
	s_barrier
	s_add_u32 s60, s64, 0x180
	s_addc_u32 s61, s65, 0
	s_mov_b32 m0, s51
	ds_read_b128 v[182:185], v217 offset:49152
	ds_read_b128 v[186:189], v217 offset:50176
	ds_read_b128 v[190:193], v217 offset:51200
	ds_read_b128 v[194:197], v217 offset:52224
	s_nop 0
	global_load_lds_dwordx4 v132, s[60:61]
	s_mov_b32 m0, s52
	s_nop 0
	global_load_lds_dwordx4 v130, s[60:61]
	s_barrier
	s_waitcnt lgkmcnt(0)
	s_setprio 3
	s_waitcnt lgkmcnt(0)
	v_mfma_f32_16x16x32_bf16 v[14:17], v[150:153], v[182:185], v[14:17]
	v_mfma_f32_16x16x32_bf16 v[26:29], v[150:153], v[190:193], v[26:29]
	v_mfma_f32_16x16x32_bf16 v[38:41], v[158:161], v[182:185], v[38:41]
	v_mfma_f32_16x16x32_bf16 v[50:53], v[158:161], v[190:193], v[50:53]
	v_mfma_f32_16x16x32_bf16 v[62:65], v[166:169], v[182:185], v[62:65]
	v_mfma_f32_16x16x32_bf16 v[74:77], v[166:169], v[190:193], v[74:77]
	v_mfma_f32_16x16x32_bf16 v[82:85], v[174:177], v[182:185], v[82:85]
	v_mfma_f32_16x16x32_bf16 v[94:97], v[174:177], v[190:193], v[94:97]
	v_mfma_f32_16x16x32_bf16 v[14:17], v[154:157], v[186:189], v[14:17]
	v_mfma_f32_16x16x32_bf16 v[26:29], v[154:157], v[194:197], v[26:29]
	v_mfma_f32_16x16x32_bf16 v[38:41], v[162:165], v[186:189], v[38:41]
	v_mfma_f32_16x16x32_bf16 v[50:53], v[162:165], v[194:197], v[50:53]
	v_mfma_f32_16x16x32_bf16 v[62:65], v[170:173], v[186:189], v[62:65]
	v_mfma_f32_16x16x32_bf16 v[74:77], v[170:173], v[194:197], v[74:77]
	v_mfma_f32_16x16x32_bf16 v[82:85], v[178:181], v[186:189], v[82:85]
	v_mfma_f32_16x16x32_bf16 v[94:97], v[178:181], v[194:197], v[94:97]
	s_setprio 0
	s_add_u32 s60, s66, 0x180
	s_addc_u32 s61, s67, 0
	s_mov_b32 m0, s53
	s_barrier
	ds_read_b128 v[150:153], v216 offset:49152
	ds_read_b128 v[154:157], v216 offset:50176
	ds_read_b128 v[158:161], v216 offset:51200
	ds_read_b128 v[162:165], v216 offset:52224
	ds_read_b128 v[166:169], v216 offset:53248
	ds_read_b128 v[170:173], v216 offset:54272
	ds_read_b128 v[174:177], v216 offset:55296
	ds_read_b128 v[178:181], v216 offset:56320
	s_nop 0
	global_load_lds_dwordx4 v132, s[60:61]
	s_mov_b32 m0, s54
	s_nop 0
	global_load_lds_dwordx4 v130, s[60:61]
	s_barrier
	s_waitcnt lgkmcnt(0)
	s_setprio 3
	s_waitcnt lgkmcnt(0)
	v_mfma_f32_16x16x32_bf16 v[18:21], v[150:153], v[134:137], v[18:21]
	v_mfma_f32_16x16x32_bf16 v[30:33], v[150:153], v[142:145], v[30:33]
	v_mfma_f32_16x16x32_bf16 v[42:45], v[158:161], v[134:137], v[42:45]
	v_mfma_f32_16x16x32_bf16 v[54:57], v[158:161], v[142:145], v[54:57]
	v_mfma_f32_16x16x32_bf16 v[66:69], v[166:169], v[134:137], v[66:69]
	v_mfma_f32_16x16x32_bf16 v[78:81], v[166:169], v[142:145], v[78:81]
	v_mfma_f32_16x16x32_bf16 v[86:89], v[174:177], v[134:137], v[86:89]
	v_mfma_f32_16x16x32_bf16 v[98:101], v[174:177], v[142:145], v[98:101]
	v_mfma_f32_16x16x32_bf16 v[18:21], v[154:157], v[138:141], v[18:21]
	v_mfma_f32_16x16x32_bf16 v[30:33], v[154:157], v[146:149], v[30:33]
	v_mfma_f32_16x16x32_bf16 v[42:45], v[162:165], v[138:141], v[42:45]
	v_mfma_f32_16x16x32_bf16 v[54:57], v[162:165], v[146:149], v[54:57]
	v_mfma_f32_16x16x32_bf16 v[66:69], v[170:173], v[138:141], v[66:69]
	v_mfma_f32_16x16x32_bf16 v[78:81], v[170:173], v[146:149], v[78:81]
	v_mfma_f32_16x16x32_bf16 v[86:89], v[178:181], v[138:141], v[86:89]
	v_mfma_f32_16x16x32_bf16 v[98:101], v[178:181], v[146:149], v[98:101]
	s_setprio 0
	s_barrier
	s_add_u32 s60, s68, 0x180
	s_addc_u32 s61, s69, 0
	s_mov_b32 m0, s55
	s_nop 0
	global_load_lds_dwordx4 v132, s[60:61]
	s_mov_b32 m0, s56
	s_nop 0
	global_load_lds_dwordx4 v130, s[60:61]
	s_waitcnt vmcnt(6)
	s_barrier
	s_setprio 3
	v_mfma_f32_16x16x32_bf16 v[90:93], v[150:153], v[182:185], v[90:93]
	v_mfma_f32_16x16x32_bf16 v[102:105], v[150:153], v[190:193], v[102:105]
	v_mfma_f32_16x16x32_bf16 v[106:109], v[158:161], v[182:185], v[106:109]
	v_mfma_f32_16x16x32_bf16 v[110:113], v[158:161], v[190:193], v[110:113]
	v_mfma_f32_16x16x32_bf16 v[114:117], v[166:169], v[182:185], v[114:117]
	v_mfma_f32_16x16x32_bf16 v[118:121], v[166:169], v[190:193], v[118:121]
	v_mfma_f32_16x16x32_bf16 v[122:125], v[174:177], v[182:185], v[122:125]
	v_mfma_f32_16x16x32_bf16 v[126:129], v[174:177], v[190:193], v[126:129]
	v_mfma_f32_16x16x32_bf16 v[90:93], v[154:157], v[186:189], v[90:93]
	v_mfma_f32_16x16x32_bf16 v[102:105], v[154:157], v[194:197], v[102:105]
	v_mfma_f32_16x16x32_bf16 v[106:109], v[162:165], v[186:189], v[106:109]
	v_mfma_f32_16x16x32_bf16 v[110:113], v[162:165], v[194:197], v[110:113]
	v_mfma_f32_16x16x32_bf16 v[114:117], v[170:173], v[186:189], v[114:117]
	v_mfma_f32_16x16x32_bf16 v[118:121], v[170:173], v[194:197], v[118:121]
	v_mfma_f32_16x16x32_bf16 v[122:125], v[178:181], v[186:189], v[122:125]
	v_mfma_f32_16x16x32_bf16 v[126:129], v[178:181], v[194:197], v[126:129]
	s_setprio 0
	s_add_u32 s30, s30, 0x100
	s_addc_u32 s31, s31, 0
	s_cmp_ge_u32 s57, s36
	s_barrier
	s_cbranch_scc0 .LBB0_403
	s_add_u32 s22, s28, s14
	s_addc_u32 s23, s29, s15
	s_mov_b32 m0, s59
	ds_read_b128 v[134:137], v217
	ds_read_b128 v[138:141], v217 offset:1024
	ds_read_b128 v[142:145], v217 offset:2048
	ds_read_b128 v[146:149], v217 offset:3072
	ds_read_b128 v[150:153], v216
	ds_read_b128 v[154:157], v216 offset:1024
	ds_read_b128 v[158:161], v216 offset:2048
	ds_read_b128 v[162:165], v216 offset:3072
	ds_read_b128 v[166:169], v216 offset:4096
	ds_read_b128 v[170:173], v216 offset:5120
	ds_read_b128 v[174:177], v216 offset:6144
	ds_read_b128 v[178:181], v216 offset:7168
	s_nop 0
	global_load_lds_dwordx4 v132, s[22:23]
	s_mov_b32 m0, s58
	s_nop 0
	global_load_lds_dwordx4 v130, s[22:23]
	s_barrier
	s_waitcnt lgkmcnt(0)
	s_setprio 3
	s_waitcnt lgkmcnt(0)
	v_mfma_f32_16x16x32_bf16 v[2:5], v[150:153], v[134:137], v[2:5]
	v_mfma_f32_16x16x32_bf16 v[6:9], v[150:153], v[142:145], v[6:9]
	v_mfma_f32_16x16x32_bf16 v[10:13], v[158:161], v[134:137], v[10:13]
	v_mfma_f32_16x16x32_bf16 v[22:25], v[158:161], v[142:145], v[22:25]
	v_mfma_f32_16x16x32_bf16 v[34:37], v[166:169], v[134:137], v[34:37]
	v_mfma_f32_16x16x32_bf16 v[46:49], v[166:169], v[142:145], v[46:49]
	v_mfma_f32_16x16x32_bf16 v[58:61], v[174:177], v[134:137], v[58:61]
	v_mfma_f32_16x16x32_bf16 v[70:73], v[174:177], v[142:145], v[70:73]
	v_mfma_f32_16x16x32_bf16 v[2:5], v[154:157], v[138:141], v[2:5]
	v_mfma_f32_16x16x32_bf16 v[6:9], v[154:157], v[146:149], v[6:9]
	v_mfma_f32_16x16x32_bf16 v[10:13], v[162:165], v[138:141], v[10:13]
	v_mfma_f32_16x16x32_bf16 v[22:25], v[162:165], v[146:149], v[22:25]
	v_mfma_f32_16x16x32_bf16 v[34:37], v[170:173], v[138:141], v[34:37]
	v_mfma_f32_16x16x32_bf16 v[46:49], v[170:173], v[146:149], v[46:49]
	v_mfma_f32_16x16x32_bf16 v[58:61], v[178:181], v[138:141], v[58:61]
	v_mfma_f32_16x16x32_bf16 v[70:73], v[178:181], v[146:149], v[70:73]
	s_setprio 0
	s_barrier
	ds_read_b128 v[182:185], v217 offset:16384
	ds_read_b128 v[186:189], v217 offset:17408
	ds_read_b128 v[190:193], v217 offset:18432
	ds_read_b128 v[194:197], v217 offset:19456
	s_barrier
	s_waitcnt lgkmcnt(0)
	s_setprio 3
	s_waitcnt lgkmcnt(0)
	v_mfma_f32_16x16x32_bf16 v[74:77], v[166:169], v[190:193], v[74:77]
	v_mfma_f32_16x16x32_bf16 v[14:17], v[150:153], v[182:185], v[14:17]
	v_mfma_f32_16x16x32_bf16 v[26:29], v[150:153], v[190:193], v[26:29]
	v_mfma_f32_16x16x32_bf16 v[38:41], v[158:161], v[182:185], v[38:41]
	v_mfma_f32_16x16x32_bf16 v[50:53], v[158:161], v[190:193], v[50:53]
	v_mfma_f32_16x16x32_bf16 v[62:65], v[166:169], v[182:185], v[62:65]
	v_mfma_f32_16x16x32_bf16 v[150:153], v[170:173], v[194:197], v[74:77]
	v_mfma_f32_16x16x32_bf16 v[74:77], v[174:177], v[182:185], v[82:85]
	v_mfma_f32_16x16x32_bf16 v[14:17], v[154:157], v[186:189], v[14:17]
	v_mfma_f32_16x16x32_bf16 v[26:29], v[154:157], v[194:197], v[26:29]
	v_mfma_f32_16x16x32_bf16 v[38:41], v[162:165], v[186:189], v[38:41]
	v_mfma_f32_16x16x32_bf16 v[50:53], v[162:165], v[194:197], v[50:53]
	v_mfma_f32_16x16x32_bf16 v[62:65], v[170:173], v[186:189], v[62:65]
	v_mfma_f32_16x16x32_bf16 v[154:157], v[178:181], v[186:189], v[74:77]
	v_mfma_f32_16x16x32_bf16 v[74:77], v[174:177], v[190:193], v[94:97]
	v_mfma_f32_16x16x32_bf16 v[158:161], v[178:181], v[194:197], v[74:77]
	s_setprio 0
	s_barrier
	s_nop 4
	ds_read_b128 v[74:77], v216 offset:16384
	ds_read_b128 v[82:85], v216 offset:17408
	ds_read_b128 v[94:97], v216 offset:18432
	ds_read_b128 v[162:165], v216 offset:19456
	ds_read_b128 v[166:169], v216 offset:20480
	ds_read_b128 v[170:173], v216 offset:21504
	ds_read_b128 v[174:177], v216 offset:22528
	ds_read_b128 v[178:181], v216 offset:23552
	s_waitcnt vmcnt(4)
	s_barrier
	s_waitcnt lgkmcnt(0)
	s_setprio 3
	s_waitcnt lgkmcnt(0)
	v_mfma_f32_16x16x32_bf16 v[66:69], v[166:169], v[134:137], v[66:69]
	v_mfma_f32_16x16x32_bf16 v[198:201], v[170:173], v[138:141], v[66:69]
	v_mfma_f32_16x16x32_bf16 v[66:69], v[166:169], v[142:145], v[78:81]
	v_mfma_f32_16x16x32_bf16 v[18:21], v[74:77], v[134:137], v[18:21]
	v_mfma_f32_16x16x32_bf16 v[30:33], v[74:77], v[142:145], v[30:33]
	v_mfma_f32_16x16x32_bf16 v[42:45], v[94:97], v[134:137], v[42:45]
	v_mfma_f32_16x16x32_bf16 v[54:57], v[94:97], v[142:145], v[54:57]
	v_mfma_f32_16x16x32_bf16 v[202:205], v[170:173], v[146:149], v[66:69]
	v_mfma_f32_16x16x32_bf16 v[66:69], v[174:177], v[134:137], v[86:89]
	v_mfma_f32_16x16x32_bf16 v[18:21], v[82:85], v[138:141], v[18:21]
	v_mfma_f32_16x16x32_bf16 v[30:33], v[82:85], v[146:149], v[30:33]
	v_mfma_f32_16x16x32_bf16 v[42:45], v[162:165], v[138:141], v[42:45]
	v_mfma_f32_16x16x32_bf16 v[54:57], v[162:165], v[146:149], v[54:57]
	v_mfma_f32_16x16x32_bf16 v[134:137], v[178:181], v[138:141], v[66:69]
	v_mfma_f32_16x16x32_bf16 v[66:69], v[174:177], v[142:145], v[98:101]
	v_mfma_f32_16x16x32_bf16 v[138:141], v[178:181], v[146:149], v[66:69]
	s_setprio 0
	s_setprio 3
	v_mfma_f32_16x16x32_bf16 v[66:69], v[74:77], v[182:185], v[90:93]
	v_mfma_f32_16x16x32_bf16 v[142:145], v[82:85], v[186:189], v[66:69]
	v_mfma_f32_16x16x32_bf16 v[66:69], v[74:77], v[190:193], v[102:105]
	v_mfma_f32_16x16x32_bf16 v[146:149], v[82:85], v[194:197], v[66:69]
	v_mfma_f32_16x16x32_bf16 v[66:69], v[94:97], v[182:185], v[106:109]
	v_mfma_f32_16x16x32_bf16 v[212:215], v[162:165], v[186:189], v[66:69]
	v_mfma_f32_16x16x32_bf16 v[66:69], v[94:97], v[190:193], v[110:113]
	v_mfma_f32_16x16x32_bf16 v[162:165], v[162:165], v[194:197], v[66:69]
	v_mfma_f32_16x16x32_bf16 v[66:69], v[166:169], v[182:185], v[114:117]
	v_mfma_f32_16x16x32_bf16 v[220:223], v[170:173], v[186:189], v[66:69]
	v_mfma_f32_16x16x32_bf16 v[66:69], v[166:169], v[190:193], v[118:121]
	v_mfma_f32_16x16x32_bf16 v[166:169], v[170:173], v[194:197], v[66:69]
	v_mfma_f32_16x16x32_bf16 v[66:69], v[174:177], v[182:185], v[122:125]
	v_mfma_f32_16x16x32_bf16 v[170:173], v[178:181], v[186:189], v[66:69]
	v_mfma_f32_16x16x32_bf16 v[66:69], v[174:177], v[190:193], v[126:129]
	v_mfma_f32_16x16x32_bf16 v[174:177], v[178:181], v[194:197], v[66:69]
	s_setprio 0
	s_barrier
	ds_read_b128 v[178:181], v217 offset:32768
	ds_read_b128 v[182:185], v217 offset:33792
	ds_read_b128 v[186:189], v217 offset:34816
	ds_read_b128 v[190:193], v217 offset:35840
	s_nop 0
	ds_read_b128 v[66:69], v216 offset:32768
	ds_read_b128 v[82:85], v216 offset:33792
	ds_read_b128 v[86:89], v216 offset:34816
	ds_read_b128 v[102:105], v216 offset:35840
	ds_read_b128 v[194:197], v216 offset:36864
	ds_read_b128 v[224:227], v216 offset:37888
	ds_read_b128 v[228:231], v216 offset:38912
	ds_read_b128 v[232:235], v216 offset:39936
	s_waitcnt vmcnt(2)
	s_barrier
	s_waitcnt lgkmcnt(0)
	s_setprio 3
	s_waitcnt lgkmcnt(0)
	v_mfma_f32_16x16x32_bf16 v[2:5], v[66:69], v[178:181], v[2:5]
	v_mfma_f32_16x16x32_bf16 v[122:125], v[82:85], v[182:185], v[2:5]
	v_mfma_f32_16x16x32_bf16 v[2:5], v[66:69], v[186:189], v[6:9]
	v_mfma_f32_16x16x32_bf16 v[126:129], v[82:85], v[190:193], v[2:5]
	v_mfma_f32_16x16x32_bf16 v[2:5], v[86:89], v[178:181], v[10:13]
	v_mfma_f32_16x16x32_bf16 v[106:109], v[102:105], v[182:185], v[2:5]
	v_mfma_f32_16x16x32_bf16 v[2:5], v[86:89], v[186:189], v[22:25]
	v_mfma_f32_16x16x32_bf16 v[110:113], v[102:105], v[190:193], v[2:5]
	v_mfma_f32_16x16x32_bf16 v[2:5], v[194:197], v[178:181], v[34:37]
	v_mfma_f32_16x16x32_bf16 v[90:93], v[224:227], v[182:185], v[2:5]
	v_mfma_f32_16x16x32_bf16 v[2:5], v[194:197], v[186:189], v[46:49]
	v_mfma_f32_16x16x32_bf16 v[94:97], v[224:227], v[190:193], v[2:5]
	v_mfma_f32_16x16x32_bf16 v[2:5], v[228:231], v[178:181], v[58:61]
	v_mfma_f32_16x16x32_bf16 v[74:77], v[232:235], v[182:185], v[2:5]
	v_mfma_f32_16x16x32_bf16 v[2:5], v[228:231], v[186:189], v[70:73]
	v_mfma_f32_16x16x32_bf16 v[78:81], v[232:235], v[190:193], v[2:5]
	s_setprio 0
	s_barrier
	s_nop 4
	ds_read_b128 v[2:5], v217 offset:49152
	ds_read_b128 v[6:9], v217 offset:50176
	ds_read_b128 v[236:239], v217 offset:51200
	ds_read_b128 v[240:243], v217 offset:52224
	s_waitcnt vmcnt(0)
	s_barrier
	s_waitcnt lgkmcnt(0)
	s_setprio 3
	s_waitcnt lgkmcnt(0)
	v_mfma_f32_16x16x32_bf16 v[10:13], v[66:69], v[2:5], v[14:17]
	v_mfma_f32_16x16x32_bf16 v[114:117], v[82:85], v[6:9], v[10:13]
	v_mfma_f32_16x16x32_bf16 v[10:13], v[66:69], v[236:239], v[26:29]
	v_mfma_f32_16x16x32_bf16 v[118:121], v[82:85], v[240:243], v[10:13]
	v_mfma_f32_16x16x32_bf16 v[10:13], v[86:89], v[2:5], v[38:41]
	v_mfma_f32_16x16x32_bf16 v[98:101], v[102:105], v[6:9], v[10:13]
	v_mfma_f32_16x16x32_bf16 v[10:13], v[86:89], v[236:239], v[50:53]
	v_mfma_f32_16x16x32_bf16 v[102:105], v[102:105], v[240:243], v[10:13]
	v_mfma_f32_16x16x32_bf16 v[10:13], v[194:197], v[2:5], v[62:65]
	v_mfma_f32_16x16x32_bf16 v[82:85], v[224:227], v[6:9], v[10:13]
	v_mfma_f32_16x16x32_bf16 v[10:13], v[194:197], v[236:239], v[150:153]
	v_mfma_f32_16x16x32_bf16 v[86:89], v[224:227], v[240:243], v[10:13]
	v_mfma_f32_16x16x32_bf16 v[10:13], v[228:231], v[2:5], v[154:157]
	v_mfma_f32_16x16x32_bf16 v[66:69], v[232:235], v[6:9], v[10:13]
	v_mfma_f32_16x16x32_bf16 v[10:13], v[228:231], v[236:239], v[158:161]
	v_mfma_f32_16x16x32_bf16 v[70:73], v[232:235], v[240:243], v[10:13]
	s_setprio 0
	s_barrier
	ds_read_b128 v[22:25], v216 offset:49152
	ds_read_b128 v[34:37], v216 offset:50176
	ds_read_b128 v[38:41], v216 offset:51200
	ds_read_b128 v[150:153], v216 offset:52224
	ds_read_b128 v[154:157], v216 offset:53248
	ds_read_b128 v[158:161], v216 offset:54272
	ds_read_b128 v[194:197], v216 offset:55296
	ds_read_b128 v[224:227], v216 offset:56320
	s_barrier
	s_waitcnt lgkmcnt(0)
	s_setprio 3
	s_waitcnt lgkmcnt(0)
	v_mfma_f32_16x16x32_bf16 v[10:13], v[22:25], v[178:181], v[18:21]
	v_mfma_f32_16x16x32_bf16 v[58:61], v[34:37], v[182:185], v[10:13]
	v_mfma_f32_16x16x32_bf16 v[10:13], v[22:25], v[186:189], v[30:33]
	v_mfma_f32_16x16x32_bf16 v[62:65], v[34:37], v[190:193], v[10:13]
	v_mfma_f32_16x16x32_bf16 v[10:13], v[38:41], v[178:181], v[42:45]
	v_mfma_f32_16x16x32_bf16 v[42:45], v[150:153], v[182:185], v[10:13]
	v_mfma_f32_16x16x32_bf16 v[10:13], v[38:41], v[186:189], v[54:57]
	v_mfma_f32_16x16x32_bf16 v[46:49], v[150:153], v[190:193], v[10:13]
	v_mfma_f32_16x16x32_bf16 v[10:13], v[154:157], v[178:181], v[198:201]
	v_mfma_f32_16x16x32_bf16 v[26:29], v[158:161], v[182:185], v[10:13]
	v_mfma_f32_16x16x32_bf16 v[10:13], v[154:157], v[186:189], v[202:205]
	v_mfma_f32_16x16x32_bf16 v[30:33], v[158:161], v[190:193], v[10:13]
	v_mfma_f32_16x16x32_bf16 v[10:13], v[194:197], v[178:181], v[134:137]
	v_mfma_f32_16x16x32_bf16 v[14:17], v[194:197], v[186:189], v[138:141]
	v_mfma_f32_16x16x32_bf16 v[10:13], v[224:227], v[182:185], v[10:13]
	v_mfma_f32_16x16x32_bf16 v[14:17], v[224:227], v[190:193], v[14:17]
	s_setprio 0
	s_setprio 3
	v_mfma_f32_16x16x32_bf16 v[18:21], v[22:25], v[2:5], v[142:145]
	v_mfma_f32_16x16x32_bf16 v[50:53], v[34:37], v[6:9], v[18:21]
	v_mfma_f32_16x16x32_bf16 v[18:21], v[22:25], v[236:239], v[146:149]
	v_mfma_f32_16x16x32_bf16 v[54:57], v[34:37], v[240:243], v[18:21]
	v_mfma_f32_16x16x32_bf16 v[18:21], v[38:41], v[2:5], v[212:215]
	v_mfma_f32_16x16x32_bf16 v[34:37], v[150:153], v[6:9], v[18:21]
	v_mfma_f32_16x16x32_bf16 v[18:21], v[38:41], v[236:239], v[162:165]
	v_mfma_f32_16x16x32_bf16 v[38:41], v[150:153], v[240:243], v[18:21]
	v_mfma_f32_16x16x32_bf16 v[18:21], v[154:157], v[2:5], v[220:223]
	v_mfma_f32_16x16x32_bf16 v[2:5], v[194:197], v[2:5], v[170:173]
	v_mfma_f32_16x16x32_bf16 v[18:21], v[158:161], v[6:9], v[18:21]
	v_mfma_f32_16x16x32_bf16 v[22:25], v[154:157], v[236:239], v[166:169]
	v_mfma_f32_16x16x32_bf16 v[2:5], v[224:227], v[6:9], v[2:5]
	v_mfma_f32_16x16x32_bf16 v[6:9], v[194:197], v[236:239], v[174:177]
	v_mfma_f32_16x16x32_bf16 v[22:25], v[158:161], v[240:243], v[22:25]
	v_mfma_f32_16x16x32_bf16 v[6:9], v[224:227], v[240:243], v[6:9]
	s_setprio 0
	s_and_b64 vcc, exec, s[16:17]
	s_barrier
	s_cbranch_vccz .LBB0_406
	s_barrier

.LBB0_457:
	s_or_b64 exec, exec, s[18:19]
	s_mulk_i32 s13, 0xff50
	s_add_i32 s13, s13, s49
	s_lshl_b32 s13, s13, 5
	s_and_b32 s18, s13, 0xffffff00
	s_ashr_i32 s19, s18, 31
	s_lshl_b64 s[52:53], s[18:19], 11
	s_add_u32 s52, s22, s52
	s_addc_u32 s53, s23, s53
	s_mov_b64 s[54:55], s[52:53]
	s_mov_b32 m0, s26
	s_ashr_i32 s17, s16, 31
	global_load_lds_dwordx4 v130, s[54:55]
	v_lshl_add_u64 v[134:135], s[54:55], 0, v[132:133]
	s_lshl_b64 s[54:55], s[16:17], 11
	s_add_u32 s54, s20, s54
	s_addc_u32 s55, s21, s55
	s_bitset1_b32 s18, 7
	s_ashr_i32 s19, s18, 31
	s_lshl_b64 s[18:19], s[18:19], 11
	s_add_u32 s18, s22, s18
	s_addc_u32 s19, s23, s19
	s_bitset1_b32 s16, 7
	s_mov_b32 m0, s27
	s_mov_b64 s[56:57], s[54:55]
	s_ashr_i32 s17, s16, 31
	global_load_lds_dwordx4 v[134:135], off
	s_mov_b32 m0, s25
	v_lshl_add_u64 v[134:135], s[56:57], 0, v[130:131]
	s_lshl_b64 s[16:17], s[16:17], 11
	global_load_lds_dwordx4 v[134:135], off
	v_lshl_add_u64 v[134:135], s[56:57], 0, v[132:133]
	s_mov_b32 m0, s28
	s_mov_b64 s[56:57], s[18:19]
	s_add_u32 s16, s20, s16
	global_load_lds_dwordx4 v[134:135], off
	s_mov_b32 m0, s29
	v_lshl_add_u64 v[134:135], s[56:57], 0, v[130:131]
	s_addc_u32 s17, s21, s17
	global_load_lds_dwordx4 v[134:135], off
	v_lshl_add_u64 v[134:135], s[56:57], 0, v[132:133]
	s_mov_b32 m0, s30
	s_mov_b64 s[56:57], s[16:17]
	global_load_lds_dwordx4 v[134:135], off
	s_mov_b32 m0, s31
	v_lshl_add_u64 v[134:135], s[56:57], 0, v[130:131]
	s_add_u32 s52, s52, 0x80
	global_load_lds_dwordx4 v[134:135], off
	v_lshl_add_u64 v[134:135], s[56:57], 0, v[132:133]
	s_mov_b32 m0, s33
	s_addc_u32 s53, s53, 0
	global_load_lds_dwordx4 v[134:135], off
	s_mov_b32 m0, s34
	global_load_lds_dwordx4 v130, s[52:53]
	v_lshl_add_u64 v[134:135], s[52:53], 0, v[132:133]
	s_add_u32 s52, s54, 0x80
	s_mov_b32 m0, s35
	s_addc_u32 s53, s55, 0
	global_load_lds_dwordx4 v[134:135], off
	s_mov_b32 m0, s36
	v_lshl_add_u64 v[134:135], s[52:53], 0, v[130:131]
	s_add_u32 s18, s18, 0x80
	global_load_lds_dwordx4 v[134:135], off
	v_lshl_add_u64 v[134:135], s[52:53], 0, v[132:133]
	s_mov_b32 m0, s37
	s_addc_u32 s19, s19, 0
	global_load_lds_dwordx4 v[134:135], off
	s_mov_b32 m0, s38
	v_lshl_add_u64 v[134:135], s[18:19], 0, v[130:131]
	s_add_u32 s16, s16, 0x80
	global_load_lds_dwordx4 v[134:135], off
	v_lshl_add_u64 v[134:135], s[18:19], 0, v[132:133]
	s_mov_b32 m0, s39
	s_addc_u32 s17, s17, 0
	global_load_lds_dwordx4 v[134:135], off
	s_mov_b32 m0, s40
	global_load_lds_dwordx4 v130, s[16:17]
	s_mov_b32 m0, s41
	s_nop 0
	global_load_lds_dwordx4 v132, s[16:17]

.LBB0_467:
	s_mul_hi_i32 s12, s49, 0x2e8ba2e9
	s_lshr_b32 s13, s12, 31
	s_ashr_i32 s12, s12, 5
	s_add_i32 s12, s12, s13
	s_mul_i32 s13, s12, 0xffffff50
	s_add_i32 s13, s13, s49
	s_ashr_i32 s50, s13, 3
	s_lshl_b32 s13, s49, 8
	s_lshl_b32 s12, s12, 11
	s_and_b32 s13, s13, 0x700
	s_or_b32 s12, s12, s13
	s_or_b32 s18, s12, 0x80
	s_ashr_i32 s19, s18, 31
	s_lshl_b32 s16, s50, 8
	s_lshl_b64 s[14:15], s[18:19], 10
	s_lshl_b64 s[18:19], s[18:19], 11
	s_add_u32 s18, s20, s18
	s_addc_u32 s19, s21, s19
	s_ashr_i32 s17, s16, 31
	s_lshl_b64 s[52:53], s[16:17], 11
	s_add_u32 s51, s22, s52
	s_addc_u32 s52, s23, s53
	s_ashr_i32 s13, s12, 31
	s_barrier
	s_barrier
	s_lshl_b64 s[54:55], s[12:13], 11
	ds_read_b128 v[2:5], v137
	ds_read_b128 v[6:9], v137 offset:1024
	ds_read_b128 v[10:13], v137 offset:2048
	ds_read_b128 v[14:17], v137 offset:3072
	s_add_u32 s13, s20, s54
	s_addc_u32 s53, s21, s55
	s_bitset1_b32 s16, 7
	s_ashr_i32 s17, s16, 31
	s_lshl_b64 s[16:17], s[16:17], 11
	s_add_u32 s54, s22, s16
	s_addc_u32 s55, s23, s17
	ds_read_b128 v[18:21], v136 offset:7168
	ds_read_b128 v[22:25], v136 offset:6144
	ds_read_b128 v[26:29], v136 offset:5120
	ds_read_b128 v[30:33], v136 offset:4096
	ds_read_b128 v[34:37], v136 offset:3072
	ds_read_b128 v[38:41], v136 offset:2048
	ds_read_b128 v[42:45], v136 offset:1024
	ds_read_b128 v[46:49], v136
	s_waitcnt lgkmcnt(8)
	s_barrier
	s_waitcnt lgkmcnt(0)
	s_setprio 3
	s_waitcnt lgkmcnt(0)
	v_mfma_f32_16x16x32_bf16 v[50:53], v[46:49], v[2:5], 0
	v_mfma_f32_16x16x32_bf16 v[54:57], v[46:49], v[10:13], 0
	v_mfma_f32_16x16x32_bf16 v[58:61], v[38:41], v[2:5], 0
	v_mfma_f32_16x16x32_bf16 v[62:65], v[38:41], v[10:13], 0
	v_mfma_f32_16x16x32_bf16 v[66:69], v[30:33], v[2:5], 0
	v_mfma_f32_16x16x32_bf16 v[70:73], v[30:33], v[10:13], 0
	v_mfma_f32_16x16x32_bf16 v[74:77], v[22:25], v[2:5], 0
	v_mfma_f32_16x16x32_bf16 v[78:81], v[22:25], v[10:13], 0
	v_mfma_f32_16x16x32_bf16 v[50:53], v[42:45], v[6:9], v[50:53]
	v_mfma_f32_16x16x32_bf16 v[54:57], v[42:45], v[14:17], v[54:57]
	v_mfma_f32_16x16x32_bf16 v[58:61], v[34:37], v[6:9], v[58:61]
	v_mfma_f32_16x16x32_bf16 v[62:65], v[34:37], v[14:17], v[62:65]
	v_mfma_f32_16x16x32_bf16 v[66:69], v[26:29], v[6:9], v[66:69]
	v_mfma_f32_16x16x32_bf16 v[70:73], v[26:29], v[14:17], v[70:73]
	v_mfma_f32_16x16x32_bf16 v[74:77], v[18:21], v[6:9], v[74:77]
	v_mfma_f32_16x16x32_bf16 v[78:81], v[18:21], v[14:17], v[78:81]
	s_setprio 0
	s_barrier
	s_add_u32 s16, s51, 0x100
	s_addc_u32 s17, s52, 0
	s_mov_b32 m0, s26
	ds_read_b128 v[82:85], v137 offset:16384
	ds_read_b128 v[86:89], v137 offset:17408
	ds_read_b128 v[90:93], v137 offset:18432
	ds_read_b128 v[94:97], v137 offset:19456
	s_nop 0
	global_load_lds_dwordx4 v130, s[16:17]
	s_mov_b32 m0, s27
	s_nop 0
	global_load_lds_dwordx4 v132, s[16:17]
	s_barrier
	s_waitcnt lgkmcnt(0)
	s_setprio 3
	s_waitcnt lgkmcnt(0)
	v_mfma_f32_16x16x32_bf16 v[98:101], v[46:49], v[82:85], 0
	v_mfma_f32_16x16x32_bf16 v[46:49], v[46:49], v[90:93], 0
	v_mfma_f32_16x16x32_bf16 v[98:101], v[42:45], v[86:89], v[98:101]
	v_mfma_f32_16x16x32_bf16 v[42:45], v[42:45], v[94:97], v[46:49]
	v_mfma_f32_16x16x32_bf16 v[46:49], v[38:41], v[82:85], 0
	v_mfma_f32_16x16x32_bf16 v[38:41], v[38:41], v[90:93], 0
	v_mfma_f32_16x16x32_bf16 v[46:49], v[34:37], v[86:89], v[46:49]
	v_mfma_f32_16x16x32_bf16 v[34:37], v[34:37], v[94:97], v[38:41]
	v_mfma_f32_16x16x32_bf16 v[38:41], v[30:33], v[82:85], 0
	v_mfma_f32_16x16x32_bf16 v[30:33], v[30:33], v[90:93], 0
	v_mfma_f32_16x16x32_bf16 v[38:41], v[26:29], v[86:89], v[38:41]
	v_mfma_f32_16x16x32_bf16 v[102:105], v[26:29], v[94:97], v[30:33]
	v_mfma_f32_16x16x32_bf16 v[26:29], v[22:25], v[82:85], 0
	v_mfma_f32_16x16x32_bf16 v[22:25], v[22:25], v[90:93], 0
	v_mfma_f32_16x16x32_bf16 v[106:109], v[18:21], v[86:89], v[26:29]
	v_mfma_f32_16x16x32_bf16 v[110:113], v[18:21], v[94:97], v[22:25]
	s_setprio 0
	s_add_u32 s16, s13, 0x100
	s_addc_u32 s17, s53, 0
	s_mov_b32 m0, s25
	s_barrier
	ds_read_b128 v[18:21], v136 offset:16384
	ds_read_b128 v[22:25], v136 offset:17408
	ds_read_b128 v[26:29], v136 offset:18432
	ds_read_b128 v[30:33], v136 offset:19456
	ds_read_b128 v[114:117], v136 offset:20480
	ds_read_b128 v[118:121], v136 offset:21504
	ds_read_b128 v[122:125], v136 offset:22528
	ds_read_b128 v[126:129], v136 offset:23552
	s_nop 0
	global_load_lds_dwordx4 v130, s[16:17]
	s_mov_b32 m0, s28
	s_nop 0
	global_load_lds_dwordx4 v132, s[16:17]
	s_barrier
	s_waitcnt lgkmcnt(0)
	s_setprio 3
	s_waitcnt lgkmcnt(0)
	v_mfma_f32_16x16x32_bf16 v[142:145], v[18:21], v[2:5], 0
	v_mfma_f32_16x16x32_bf16 v[150:153], v[26:29], v[2:5], 0
	v_mfma_f32_16x16x32_bf16 v[158:161], v[114:117], v[2:5], 0
	v_mfma_f32_16x16x32_bf16 v[2:5], v[122:125], v[2:5], 0
	v_mfma_f32_16x16x32_bf16 v[146:149], v[18:21], v[10:13], 0
	v_mfma_f32_16x16x32_bf16 v[154:157], v[26:29], v[10:13], 0
	v_mfma_f32_16x16x32_bf16 v[162:165], v[114:117], v[10:13], 0
	v_mfma_f32_16x16x32_bf16 v[166:169], v[126:129], v[6:9], v[2:5]
	v_mfma_f32_16x16x32_bf16 v[2:5], v[122:125], v[10:13], 0
	v_mfma_f32_16x16x32_bf16 v[142:145], v[22:25], v[6:9], v[142:145]
	v_mfma_f32_16x16x32_bf16 v[146:149], v[22:25], v[14:17], v[146:149]
	v_mfma_f32_16x16x32_bf16 v[150:153], v[30:33], v[6:9], v[150:153]
	v_mfma_f32_16x16x32_bf16 v[154:157], v[30:33], v[14:17], v[154:157]
	v_mfma_f32_16x16x32_bf16 v[158:161], v[118:121], v[6:9], v[158:161]
	v_mfma_f32_16x16x32_bf16 v[162:165], v[118:121], v[14:17], v[162:165]
	v_mfma_f32_16x16x32_bf16 v[170:173], v[126:129], v[14:17], v[2:5]
	s_setprio 0
	s_barrier
	s_add_u32 s16, s54, 0x100
	s_addc_u32 s17, s55, 0
	s_mov_b32 m0, s29
	s_nop 0
	global_load_lds_dwordx4 v130, s[16:17]
	s_mov_b32 m0, s30
	s_nop 0
	global_load_lds_dwordx4 v132, s[16:17]
	s_waitcnt vmcnt(14)
	s_barrier
	s_setprio 3
	v_mfma_f32_16x16x32_bf16 v[2:5], v[18:21], v[82:85], 0
	v_mfma_f32_16x16x32_bf16 v[174:177], v[22:25], v[86:89], v[2:5]
	v_mfma_f32_16x16x32_bf16 v[2:5], v[18:21], v[90:93], 0
	v_mfma_f32_16x16x32_bf16 v[178:181], v[22:25], v[94:97], v[2:5]
	v_mfma_f32_16x16x32_bf16 v[2:5], v[26:29], v[82:85], 0
	v_mfma_f32_16x16x32_bf16 v[182:185], v[30:33], v[86:89], v[2:5]
	v_mfma_f32_16x16x32_bf16 v[2:5], v[26:29], v[90:93], 0
	v_mfma_f32_16x16x32_bf16 v[186:189], v[30:33], v[94:97], v[2:5]
	v_mfma_f32_16x16x32_bf16 v[2:5], v[114:117], v[82:85], 0
	v_mfma_f32_16x16x32_bf16 v[190:193], v[118:121], v[86:89], v[2:5]
	v_mfma_f32_16x16x32_bf16 v[2:5], v[114:117], v[90:93], 0
	v_mfma_f32_16x16x32_bf16 v[194:197], v[118:121], v[94:97], v[2:5]
	v_mfma_f32_16x16x32_bf16 v[2:5], v[122:125], v[82:85], 0
	v_mfma_f32_16x16x32_bf16 v[198:201], v[126:129], v[86:89], v[2:5]
	v_mfma_f32_16x16x32_bf16 v[2:5], v[122:125], v[90:93], 0
	v_mfma_f32_16x16x32_bf16 v[202:205], v[126:129], v[94:97], v[2:5]
	s_setprio 0
	s_barrier
	ds_read_b128 v[114:117], v137 offset:32768
	ds_read_b128 v[118:121], v137 offset:33792
	ds_read_b128 v[122:125], v137 offset:34816
	ds_read_b128 v[126:129], v137 offset:35840
	s_add_u32 s16, s18, 0x100
	s_addc_u32 s17, s19, 0
	s_mov_b32 m0, s31
	ds_read_b128 v[82:85], v136 offset:32768
	ds_read_b128 v[86:89], v136 offset:33792
	ds_read_b128 v[90:93], v136 offset:34816
	ds_read_b128 v[94:97], v136 offset:35840
	ds_read_b128 v[216:219], v136 offset:36864
	ds_read_b128 v[220:223], v136 offset:37888
	ds_read_b128 v[224:227], v136 offset:38912
	ds_read_b128 v[228:231], v136 offset:39936
	s_nop 0
	global_load_lds_dwordx4 v130, s[16:17]
	s_mov_b32 m0, s33
	s_nop 0
	global_load_lds_dwordx4 v132, s[16:17]
	s_waitcnt lgkmcnt(8)
	s_barrier
	s_waitcnt lgkmcnt(0)
	s_setprio 3
	s_waitcnt lgkmcnt(0)
	v_mfma_f32_16x16x32_bf16 v[2:5], v[82:85], v[114:117], v[50:53]
	v_mfma_f32_16x16x32_bf16 v[30:33], v[86:89], v[118:121], v[2:5]
	v_mfma_f32_16x16x32_bf16 v[2:5], v[82:85], v[122:125], v[54:57]
	v_mfma_f32_16x16x32_bf16 v[26:29], v[86:89], v[126:129], v[2:5]
	v_mfma_f32_16x16x32_bf16 v[2:5], v[90:93], v[114:117], v[58:61]
	v_mfma_f32_16x16x32_bf16 v[22:25], v[94:97], v[118:121], v[2:5]
	v_mfma_f32_16x16x32_bf16 v[2:5], v[90:93], v[122:125], v[62:65]
	v_mfma_f32_16x16x32_bf16 v[18:21], v[94:97], v[126:129], v[2:5]
	v_mfma_f32_16x16x32_bf16 v[2:5], v[216:219], v[114:117], v[66:69]
	v_mfma_f32_16x16x32_bf16 v[14:17], v[220:223], v[118:121], v[2:5]
	v_mfma_f32_16x16x32_bf16 v[2:5], v[216:219], v[122:125], v[70:73]
	v_mfma_f32_16x16x32_bf16 v[10:13], v[220:223], v[126:129], v[2:5]
	v_mfma_f32_16x16x32_bf16 v[2:5], v[224:227], v[114:117], v[74:77]
	v_mfma_f32_16x16x32_bf16 v[6:9], v[228:231], v[118:121], v[2:5]
	v_mfma_f32_16x16x32_bf16 v[2:5], v[224:227], v[122:125], v[78:81]
	v_mfma_f32_16x16x32_bf16 v[2:5], v[228:231], v[126:129], v[2:5]
	s_setprio 0
	s_barrier
	s_add_u32 s16, s51, 0x180
	s_addc_u32 s17, s52, 0
	s_mov_b32 m0, s34
	ds_read_b128 v[232:235], v137 offset:49152
	ds_read_b128 v[236:239], v137 offset:50176
	ds_read_b128 v[240:243], v137 offset:51200
	ds_read_b128 v[244:247], v137 offset:52224
	s_nop 0
	global_load_lds_dwordx4 v130, s[16:17]
	s_mov_b32 m0, s35
	s_nop 0
	global_load_lds_dwordx4 v132, s[16:17]
	s_barrier
	s_waitcnt lgkmcnt(0)
	s_setprio 3
	s_waitcnt lgkmcnt(0)
	v_mfma_f32_16x16x32_bf16 v[50:53], v[82:85], v[232:235], v[98:101]
	v_mfma_f32_16x16x32_bf16 v[34:37], v[90:93], v[240:243], v[34:37]
	v_mfma_f32_16x16x32_bf16 v[62:65], v[86:89], v[236:239], v[50:53]
	v_mfma_f32_16x16x32_bf16 v[42:45], v[82:85], v[240:243], v[42:45]
	v_mfma_f32_16x16x32_bf16 v[50:53], v[94:97], v[244:247], v[34:37]
	v_mfma_f32_16x16x32_bf16 v[34:37], v[216:219], v[232:235], v[38:41]
	v_mfma_f32_16x16x32_bf16 v[58:61], v[86:89], v[244:247], v[42:45]
	v_mfma_f32_16x16x32_bf16 v[42:45], v[90:93], v[232:235], v[46:49]
	v_mfma_f32_16x16x32_bf16 v[46:49], v[220:223], v[236:239], v[34:37]
	v_mfma_f32_16x16x32_bf16 v[34:37], v[216:219], v[240:243], v[102:105]
	v_mfma_f32_16x16x32_bf16 v[54:57], v[94:97], v[236:239], v[42:45]
	v_mfma_f32_16x16x32_bf16 v[42:45], v[220:223], v[244:247], v[34:37]
	v_mfma_f32_16x16x32_bf16 v[34:37], v[224:227], v[232:235], v[106:109]
	v_mfma_f32_16x16x32_bf16 v[38:41], v[228:231], v[236:239], v[34:37]
	v_mfma_f32_16x16x32_bf16 v[34:37], v[224:227], v[240:243], v[110:113]
	v_mfma_f32_16x16x32_bf16 v[34:37], v[228:231], v[244:247], v[34:37]
	s_setprio 0
	s_add_u32 s16, s13, 0x180
	s_addc_u32 s17, s53, 0
	s_mov_b32 m0, s36
	s_barrier
	ds_read_b128 v[98:101], v136 offset:49152
	ds_read_b128 v[102:105], v136 offset:50176
	ds_read_b128 v[106:109], v136 offset:51200
	ds_read_b128 v[110:113], v136 offset:52224
	ds_read_b128 v[216:219], v136 offset:53248
	ds_read_b128 v[220:223], v136 offset:54272
	ds_read_b128 v[224:227], v136 offset:55296
	ds_read_b128 v[228:231], v136 offset:56320
	s_nop 0
	global_load_lds_dwordx4 v130, s[16:17]
	s_mov_b32 m0, s37
	s_nop 0
	global_load_lds_dwordx4 v132, s[16:17]
	s_barrier
	s_waitcnt lgkmcnt(0)
	s_setprio 3
	s_waitcnt lgkmcnt(0)
	v_mfma_f32_16x16x32_bf16 v[66:69], v[98:101], v[114:117], v[142:145]
	v_mfma_f32_16x16x32_bf16 v[94:97], v[102:105], v[118:121], v[66:69]
	v_mfma_f32_16x16x32_bf16 v[66:69], v[98:101], v[122:125], v[146:149]
	v_mfma_f32_16x16x32_bf16 v[90:93], v[102:105], v[126:129], v[66:69]
	v_mfma_f32_16x16x32_bf16 v[66:69], v[106:109], v[114:117], v[150:153]
	v_mfma_f32_16x16x32_bf16 v[86:89], v[110:113], v[118:121], v[66:69]
	v_mfma_f32_16x16x32_bf16 v[66:69], v[106:109], v[122:125], v[154:157]
	v_mfma_f32_16x16x32_bf16 v[82:85], v[110:113], v[126:129], v[66:69]
	v_mfma_f32_16x16x32_bf16 v[66:69], v[216:219], v[114:117], v[158:161]
	v_mfma_f32_16x16x32_bf16 v[78:81], v[220:223], v[118:121], v[66:69]
	v_mfma_f32_16x16x32_bf16 v[66:69], v[216:219], v[122:125], v[162:165]
	v_mfma_f32_16x16x32_bf16 v[74:77], v[220:223], v[126:129], v[66:69]
	v_mfma_f32_16x16x32_bf16 v[66:69], v[224:227], v[114:117], v[166:169]
	v_mfma_f32_16x16x32_bf16 v[70:73], v[228:231], v[118:121], v[66:69]
	v_mfma_f32_16x16x32_bf16 v[66:69], v[224:227], v[122:125], v[170:173]
	v_mfma_f32_16x16x32_bf16 v[66:69], v[228:231], v[126:129], v[66:69]
	s_setprio 0
	s_barrier
	s_add_u32 s16, s54, 0x180
	s_addc_u32 s17, s55, 0
	s_mov_b32 m0, s38
	s_nop 0
	global_load_lds_dwordx4 v130, s[16:17]
	s_mov_b32 m0, s39
	s_nop 0
	global_load_lds_dwordx4 v132, s[16:17]
	s_waitcnt vmcnt(6)
	s_barrier
	s_setprio 3
	v_mfma_f32_16x16x32_bf16 v[114:117], v[98:101], v[232:235], v[174:177]
	v_mfma_f32_16x16x32_bf16 v[98:101], v[98:101], v[240:243], v[178:181]
	v_mfma_f32_16x16x32_bf16 v[122:125], v[102:105], v[244:247], v[98:101]
	v_mfma_f32_16x16x32_bf16 v[98:101], v[106:109], v[232:235], v[182:185]
	v_mfma_f32_16x16x32_bf16 v[118:121], v[110:113], v[236:239], v[98:101]
	v_mfma_f32_16x16x32_bf16 v[98:101], v[106:109], v[240:243], v[186:189]
	v_mfma_f32_16x16x32_bf16 v[126:129], v[102:105], v[236:239], v[114:117]
	v_mfma_f32_16x16x32_bf16 v[114:117], v[110:113], v[244:247], v[98:101]
	v_mfma_f32_16x16x32_bf16 v[98:101], v[216:219], v[232:235], v[190:193]
	v_mfma_f32_16x16x32_bf16 v[110:113], v[220:223], v[236:239], v[98:101]
	v_mfma_f32_16x16x32_bf16 v[98:101], v[216:219], v[240:243], v[194:197]
	v_mfma_f32_16x16x32_bf16 v[106:109], v[220:223], v[244:247], v[98:101]
	v_mfma_f32_16x16x32_bf16 v[98:101], v[224:227], v[232:235], v[198:201]
	v_mfma_f32_16x16x32_bf16 v[102:105], v[228:231], v[236:239], v[98:101]
	v_mfma_f32_16x16x32_bf16 v[98:101], v[224:227], v[240:243], v[202:205]
	v_mfma_f32_16x16x32_bf16 v[98:101], v[228:231], v[244:247], v[98:101]
	s_setprio 0
	s_mov_b32 s56, 0
	s_mov_b64 s[16:17], 0
	s_barrier
.LBB0_468:
	ds_read_b128 v[138:141], v137
	ds_read_b128 v[142:145], v137 offset:1024
	ds_read_b128 v[146:149], v137 offset:2048
	ds_read_b128 v[150:153], v137 offset:3072
	s_add_u32 s57, s18, s16
	s_addc_u32 s60, s19, s17
	s_add_u32 s58, s57, 0x180
	s_addc_u32 s59, s60, 0
	s_mov_b32 m0, s40
	ds_read_b128 v[154:157], v136
	ds_read_b128 v[158:161], v136 offset:1024
	ds_read_b128 v[162:165], v136 offset:2048
	ds_read_b128 v[166:169], v136 offset:3072
	ds_read_b128 v[170:173], v136 offset:4096
	ds_read_b128 v[174:177], v136 offset:5120
	ds_read_b128 v[178:181], v136 offset:6144
	ds_read_b128 v[182:185], v136 offset:7168
	s_nop 0
	global_load_lds_dwordx4 v130, s[58:59]
	s_mov_b32 m0, s41
	s_nop 0
	global_load_lds_dwordx4 v132, s[58:59]
	s_waitcnt lgkmcnt(8)
	s_barrier
	s_waitcnt lgkmcnt(0)
	s_setprio 3
	s_waitcnt lgkmcnt(0)
	v_mfma_f32_16x16x32_bf16 v[30:33], v[154:157], v[138:141], v[30:33]
	v_mfma_f32_16x16x32_bf16 v[26:29], v[154:157], v[146:149], v[26:29]
	v_mfma_f32_16x16x32_bf16 v[22:25], v[162:165], v[138:141], v[22:25]
	v_mfma_f32_16x16x32_bf16 v[18:21], v[162:165], v[146:149], v[18:21]
	v_mfma_f32_16x16x32_bf16 v[14:17], v[170:173], v[138:141], v[14:17]
	v_mfma_f32_16x16x32_bf16 v[10:13], v[170:173], v[146:149], v[10:13]
	v_mfma_f32_16x16x32_bf16 v[6:9], v[178:181], v[138:141], v[6:9]
	v_mfma_f32_16x16x32_bf16 v[2:5], v[178:181], v[146:149], v[2:5]
	v_mfma_f32_16x16x32_bf16 v[30:33], v[158:161], v[142:145], v[30:33]
	v_mfma_f32_16x16x32_bf16 v[26:29], v[158:161], v[150:153], v[26:29]
	v_mfma_f32_16x16x32_bf16 v[22:25], v[166:169], v[142:145], v[22:25]
	v_mfma_f32_16x16x32_bf16 v[18:21], v[166:169], v[150:153], v[18:21]
	v_mfma_f32_16x16x32_bf16 v[14:17], v[174:177], v[142:145], v[14:17]
	v_mfma_f32_16x16x32_bf16 v[10:13], v[174:177], v[150:153], v[10:13]
	v_mfma_f32_16x16x32_bf16 v[6:9], v[182:185], v[142:145], v[6:9]
	v_mfma_f32_16x16x32_bf16 v[2:5], v[182:185], v[150:153], v[2:5]
	s_setprio 0
	s_barrier
	s_add_u32 s61, s51, s16
	s_addc_u32 s62, s52, s17
	s_add_u32 s58, s61, 0x200
	s_addc_u32 s59, s62, 0
	s_mov_b32 m0, s26
	ds_read_b128 v[186:189], v137 offset:16384
	ds_read_b128 v[190:193], v137 offset:17408
	ds_read_b128 v[194:197], v137 offset:18432
	ds_read_b128 v[198:201], v137 offset:19456
	s_nop 0
	global_load_lds_dwordx4 v130, s[58:59]
	s_mov_b32 m0, s27
	s_nop 0
	global_load_lds_dwordx4 v132, s[58:59]
	s_barrier
	s_waitcnt lgkmcnt(0)
	s_setprio 3
	s_waitcnt lgkmcnt(0)
	v_mfma_f32_16x16x32_bf16 v[62:65], v[154:157], v[186:189], v[62:65]
	v_mfma_f32_16x16x32_bf16 v[58:61], v[154:157], v[194:197], v[58:61]
	v_mfma_f32_16x16x32_bf16 v[54:57], v[162:165], v[186:189], v[54:57]
	v_mfma_f32_16x16x32_bf16 v[50:53], v[162:165], v[194:197], v[50:53]
	v_mfma_f32_16x16x32_bf16 v[46:49], v[170:173], v[186:189], v[46:49]
	v_mfma_f32_16x16x32_bf16 v[42:45], v[170:173], v[194:197], v[42:45]
	v_mfma_f32_16x16x32_bf16 v[38:41], v[178:181], v[186:189], v[38:41]
	v_mfma_f32_16x16x32_bf16 v[34:37], v[178:181], v[194:197], v[34:37]
	v_mfma_f32_16x16x32_bf16 v[62:65], v[158:161], v[190:193], v[62:65]
	v_mfma_f32_16x16x32_bf16 v[58:61], v[158:161], v[198:201], v[58:61]
	v_mfma_f32_16x16x32_bf16 v[54:57], v[166:169], v[190:193], v[54:57]
	v_mfma_f32_16x16x32_bf16 v[50:53], v[166:169], v[198:201], v[50:53]
	v_mfma_f32_16x16x32_bf16 v[46:49], v[174:177], v[190:193], v[46:49]
	v_mfma_f32_16x16x32_bf16 v[42:45], v[174:177], v[198:201], v[42:45]
	v_mfma_f32_16x16x32_bf16 v[38:41], v[182:185], v[190:193], v[38:41]
	v_mfma_f32_16x16x32_bf16 v[34:37], v[182:185], v[198:201], v[34:37]
	s_setprio 0
	s_add_u32 s63, s13, s16
	s_addc_u32 s64, s53, s17
	s_add_u32 s58, s63, 0x200
	s_addc_u32 s59, s64, 0
	s_mov_b32 m0, s25
	s_barrier
	ds_read_b128 v[154:157], v136 offset:16384
	ds_read_b128 v[158:161], v136 offset:17408
	ds_read_b128 v[162:165], v136 offset:18432
	ds_read_b128 v[166:169], v136 offset:19456
	ds_read_b128 v[170:173], v136 offset:20480
	ds_read_b128 v[174:177], v136 offset:21504
	ds_read_b128 v[178:181], v136 offset:22528
	ds_read_b128 v[182:185], v136 offset:23552
	s_nop 0
	global_load_lds_dwordx4 v130, s[58:59]
	s_mov_b32 m0, s28
	s_nop 0
	global_load_lds_dwordx4 v132, s[58:59]
	s_barrier
	s_waitcnt lgkmcnt(0)
	s_setprio 3
	s_waitcnt lgkmcnt(0)
	v_mfma_f32_16x16x32_bf16 v[94:97], v[154:157], v[138:141], v[94:97]
	v_mfma_f32_16x16x32_bf16 v[90:93], v[154:157], v[146:149], v[90:93]
	v_mfma_f32_16x16x32_bf16 v[86:89], v[162:165], v[138:141], v[86:89]
	v_mfma_f32_16x16x32_bf16 v[82:85], v[162:165], v[146:149], v[82:85]
	v_mfma_f32_16x16x32_bf16 v[78:81], v[170:173], v[138:141], v[78:81]
	v_mfma_f32_16x16x32_bf16 v[74:77], v[170:173], v[146:149], v[74:77]
	v_mfma_f32_16x16x32_bf16 v[70:73], v[178:181], v[138:141], v[70:73]
	v_mfma_f32_16x16x32_bf16 v[66:69], v[178:181], v[146:149], v[66:69]
	v_mfma_f32_16x16x32_bf16 v[94:97], v[158:161], v[142:145], v[94:97]
	v_mfma_f32_16x16x32_bf16 v[90:93], v[158:161], v[150:153], v[90:93]
	v_mfma_f32_16x16x32_bf16 v[86:89], v[166:169], v[142:145], v[86:89]
	v_mfma_f32_16x16x32_bf16 v[82:85], v[166:169], v[150:153], v[82:85]
	v_mfma_f32_16x16x32_bf16 v[78:81], v[174:177], v[142:145], v[78:81]
	v_mfma_f32_16x16x32_bf16 v[74:77], v[174:177], v[150:153], v[74:77]
	v_mfma_f32_16x16x32_bf16 v[70:73], v[182:185], v[142:145], v[70:73]
	v_mfma_f32_16x16x32_bf16 v[66:69], v[182:185], v[150:153], v[66:69]
	s_setprio 0
	s_barrier
	s_add_u32 s65, s54, s16
	s_addc_u32 s66, s55, s17
	s_add_u32 s58, s65, 0x200
	s_addc_u32 s59, s66, 0
	s_mov_b32 m0, s29
	s_nop 0
	global_load_lds_dwordx4 v130, s[58:59]
	s_mov_b32 m0, s30
	s_nop 0
	global_load_lds_dwordx4 v132, s[58:59]
	s_waitcnt vmcnt(6)
	s_barrier
	s_setprio 3
	v_mfma_f32_16x16x32_bf16 v[126:129], v[154:157], v[186:189], v[126:129]
	v_mfma_f32_16x16x32_bf16 v[122:125], v[154:157], v[194:197], v[122:125]
	v_mfma_f32_16x16x32_bf16 v[118:121], v[162:165], v[186:189], v[118:121]
	v_mfma_f32_16x16x32_bf16 v[114:117], v[162:165], v[194:197], v[114:117]
	v_mfma_f32_16x16x32_bf16 v[110:113], v[170:173], v[186:189], v[110:113]
	v_mfma_f32_16x16x32_bf16 v[106:109], v[170:173], v[194:197], v[106:109]
	v_mfma_f32_16x16x32_bf16 v[102:105], v[178:181], v[186:189], v[102:105]
	v_mfma_f32_16x16x32_bf16 v[98:101], v[178:181], v[194:197], v[98:101]
	v_mfma_f32_16x16x32_bf16 v[126:129], v[158:161], v[190:193], v[126:129]
	v_mfma_f32_16x16x32_bf16 v[122:125], v[158:161], v[198:201], v[122:125]
	v_mfma_f32_16x16x32_bf16 v[118:121], v[166:169], v[190:193], v[118:121]
	v_mfma_f32_16x16x32_bf16 v[114:117], v[166:169], v[198:201], v[114:117]
	v_mfma_f32_16x16x32_bf16 v[110:113], v[174:177], v[190:193], v[110:113]
	v_mfma_f32_16x16x32_bf16 v[106:109], v[174:177], v[198:201], v[106:109]
	v_mfma_f32_16x16x32_bf16 v[102:105], v[182:185], v[190:193], v[102:105]
	v_mfma_f32_16x16x32_bf16 v[98:101], v[182:185], v[198:201], v[98:101]
	s_setprio 0
	s_barrier
	ds_read_b128 v[138:141], v137 offset:32768
	ds_read_b128 v[142:145], v137 offset:33792
	ds_read_b128 v[146:149], v137 offset:34816
	ds_read_b128 v[150:153], v137 offset:35840
	s_add_u32 s58, s57, 0x200
	s_addc_u32 s59, s60, 0
	s_mov_b32 m0, s31
	ds_read_b128 v[154:157], v136 offset:32768
	ds_read_b128 v[158:161], v136 offset:33792
	ds_read_b128 v[162:165], v136 offset:34816
	ds_read_b128 v[166:169], v136 offset:35840
	ds_read_b128 v[170:173], v136 offset:36864
	ds_read_b128 v[174:177], v136 offset:37888
	ds_read_b128 v[178:181], v136 offset:38912
	ds_read_b128 v[182:185], v136 offset:39936
	s_nop 0
	global_load_lds_dwordx4 v130, s[58:59]
	s_mov_b32 m0, s33
	s_nop 0
	global_load_lds_dwordx4 v132, s[58:59]
	s_waitcnt lgkmcnt(8)
	s_barrier
	s_waitcnt lgkmcnt(0)
	s_setprio 3
	s_waitcnt lgkmcnt(0)
	v_mfma_f32_16x16x32_bf16 v[30:33], v[154:157], v[138:141], v[30:33]
	v_mfma_f32_16x16x32_bf16 v[26:29], v[154:157], v[146:149], v[26:29]
	v_mfma_f32_16x16x32_bf16 v[22:25], v[162:165], v[138:141], v[22:25]
	v_mfma_f32_16x16x32_bf16 v[18:21], v[162:165], v[146:149], v[18:21]
	v_mfma_f32_16x16x32_bf16 v[14:17], v[170:173], v[138:141], v[14:17]
	v_mfma_f32_16x16x32_bf16 v[10:13], v[170:173], v[146:149], v[10:13]
	v_mfma_f32_16x16x32_bf16 v[6:9], v[178:181], v[138:141], v[6:9]
	v_mfma_f32_16x16x32_bf16 v[2:5], v[178:181], v[146:149], v[2:5]
	v_mfma_f32_16x16x32_bf16 v[30:33], v[158:161], v[142:145], v[30:33]
	v_mfma_f32_16x16x32_bf16 v[26:29], v[158:161], v[150:153], v[26:29]
	v_mfma_f32_16x16x32_bf16 v[22:25], v[166:169], v[142:145], v[22:25]
	v_mfma_f32_16x16x32_bf16 v[18:21], v[166:169], v[150:153], v[18:21]
	v_mfma_f32_16x16x32_bf16 v[14:17], v[174:177], v[142:145], v[14:17]
	v_mfma_f32_16x16x32_bf16 v[10:13], v[174:177], v[150:153], v[10:13]
	v_mfma_f32_16x16x32_bf16 v[6:9], v[182:185], v[142:145], v[6:9]
	v_mfma_f32_16x16x32_bf16 v[2:5], v[182:185], v[150:153], v[2:5]
	s_setprio 0
	s_barrier
	s_add_u32 s58, s61, 0x280
	s_addc_u32 s59, s62, 0
	s_mov_b32 m0, s34
	ds_read_b128 v[186:189], v137 offset:49152
	ds_read_b128 v[190:193], v137 offset:50176
	ds_read_b128 v[194:197], v137 offset:51200
	ds_read_b128 v[198:201], v137 offset:52224
	s_nop 0
	global_load_lds_dwordx4 v130, s[58:59]
	s_mov_b32 m0, s35
	s_nop 0
	global_load_lds_dwordx4 v132, s[58:59]
	s_barrier
	s_waitcnt lgkmcnt(0)
	s_setprio 3
	s_waitcnt lgkmcnt(0)
	v_mfma_f32_16x16x32_bf16 v[62:65], v[154:157], v[186:189], v[62:65]
	v_mfma_f32_16x16x32_bf16 v[58:61], v[154:157], v[194:197], v[58:61]
	v_mfma_f32_16x16x32_bf16 v[54:57], v[162:165], v[186:189], v[54:57]
	v_mfma_f32_16x16x32_bf16 v[50:53], v[162:165], v[194:197], v[50:53]
	v_mfma_f32_16x16x32_bf16 v[46:49], v[170:173], v[186:189], v[46:49]
	v_mfma_f32_16x16x32_bf16 v[42:45], v[170:173], v[194:197], v[42:45]
	v_mfma_f32_16x16x32_bf16 v[38:41], v[178:181], v[186:189], v[38:41]
	v_mfma_f32_16x16x32_bf16 v[34:37], v[178:181], v[194:197], v[34:37]
	v_mfma_f32_16x16x32_bf16 v[62:65], v[158:161], v[190:193], v[62:65]
	v_mfma_f32_16x16x32_bf16 v[58:61], v[158:161], v[198:201], v[58:61]
	v_mfma_f32_16x16x32_bf16 v[54:57], v[166:169], v[190:193], v[54:57]
	v_mfma_f32_16x16x32_bf16 v[50:53], v[166:169], v[198:201], v[50:53]
	v_mfma_f32_16x16x32_bf16 v[46:49], v[174:177], v[190:193], v[46:49]
	v_mfma_f32_16x16x32_bf16 v[42:45], v[174:177], v[198:201], v[42:45]
	v_mfma_f32_16x16x32_bf16 v[38:41], v[182:185], v[190:193], v[38:41]
	v_mfma_f32_16x16x32_bf16 v[34:37], v[182:185], v[198:201], v[34:37]
	s_setprio 0
	s_add_u32 s58, s63, 0x280
	s_addc_u32 s59, s64, 0
	s_mov_b32 m0, s36
	s_barrier
	ds_read_b128 v[154:157], v136 offset:49152
	ds_read_b128 v[158:161], v136 offset:50176
	ds_read_b128 v[162:165], v136 offset:51200
	ds_read_b128 v[166:169], v136 offset:52224
	ds_read_b128 v[170:173], v136 offset:53248
	ds_read_b128 v[174:177], v136 offset:54272
	ds_read_b128 v[178:181], v136 offset:55296
	ds_read_b128 v[182:185], v136 offset:56320
	s_nop 0
	global_load_lds_dwordx4 v130, s[58:59]
	s_mov_b32 m0, s37
	s_nop 0
	global_load_lds_dwordx4 v132, s[58:59]
	s_barrier
	s_waitcnt lgkmcnt(0)
	s_setprio 3
	s_waitcnt lgkmcnt(0)
	v_mfma_f32_16x16x32_bf16 v[94:97], v[154:157], v[138:141], v[94:97]
	v_mfma_f32_16x16x32_bf16 v[90:93], v[154:157], v[146:149], v[90:93]
	v_mfma_f32_16x16x32_bf16 v[86:89], v[162:165], v[138:141], v[86:89]
	v_mfma_f32_16x16x32_bf16 v[82:85], v[162:165], v[146:149], v[82:85]
	v_mfma_f32_16x16x32_bf16 v[78:81], v[170:173], v[138:141], v[78:81]
	v_mfma_f32_16x16x32_bf16 v[74:77], v[170:173], v[146:149], v[74:77]
	v_mfma_f32_16x16x32_bf16 v[70:73], v[178:181], v[138:141], v[70:73]
	v_mfma_f32_16x16x32_bf16 v[66:69], v[178:181], v[146:149], v[66:69]
	v_mfma_f32_16x16x32_bf16 v[94:97], v[158:161], v[142:145], v[94:97]
	v_mfma_f32_16x16x32_bf16 v[90:93], v[158:161], v[150:153], v[90:93]
	v_mfma_f32_16x16x32_bf16 v[86:89], v[166:169], v[142:145], v[86:89]
	v_mfma_f32_16x16x32_bf16 v[82:85], v[166:169], v[150:153], v[82:85]
	v_mfma_f32_16x16x32_bf16 v[78:81], v[174:177], v[142:145], v[78:81]
	v_mfma_f32_16x16x32_bf16 v[74:77], v[174:177], v[150:153], v[74:77]
	v_mfma_f32_16x16x32_bf16 v[70:73], v[182:185], v[142:145], v[70:73]
	v_mfma_f32_16x16x32_bf16 v[66:69], v[182:185], v[150:153], v[66:69]
	s_setprio 0
	s_barrier
	s_add_u32 s58, s65, 0x280
	s_addc_u32 s59, s66, 0
	s_mov_b32 m0, s38
	s_nop 0
	global_load_lds_dwordx4 v130, s[58:59]
	s_mov_b32 m0, s39
	s_nop 0
	global_load_lds_dwordx4 v132, s[58:59]
	s_waitcnt vmcnt(6)
	s_barrier
	s_setprio 3
	v_mfma_f32_16x16x32_bf16 v[126:129], v[154:157], v[186:189], v[126:129]
	v_mfma_f32_16x16x32_bf16 v[122:125], v[154:157], v[194:197], v[122:125]
	v_mfma_f32_16x16x32_bf16 v[118:121], v[162:165], v[186:189], v[118:121]
	v_mfma_f32_16x16x32_bf16 v[114:117], v[162:165], v[194:197], v[114:117]
	v_mfma_f32_16x16x32_bf16 v[110:113], v[170:173], v[186:189], v[110:113]
	v_mfma_f32_16x16x32_bf16 v[106:109], v[170:173], v[194:197], v[106:109]
	v_mfma_f32_16x16x32_bf16 v[102:105], v[178:181], v[186:189], v[102:105]
	v_mfma_f32_16x16x32_bf16 v[98:101], v[178:181], v[194:197], v[98:101]
	v_mfma_f32_16x16x32_bf16 v[126:129], v[158:161], v[190:193], v[126:129]
	v_mfma_f32_16x16x32_bf16 v[122:125], v[158:161], v[198:201], v[122:125]
	v_mfma_f32_16x16x32_bf16 v[118:121], v[166:169], v[190:193], v[118:121]
	v_mfma_f32_16x16x32_bf16 v[114:117], v[166:169], v[198:201], v[114:117]
	v_mfma_f32_16x16x32_bf16 v[110:113], v[174:177], v[190:193], v[110:113]
	v_mfma_f32_16x16x32_bf16 v[106:109], v[174:177], v[198:201], v[106:109]
	v_mfma_f32_16x16x32_bf16 v[102:105], v[182:185], v[190:193], v[102:105]
	v_mfma_f32_16x16x32_bf16 v[98:101], v[182:185], v[198:201], v[98:101]
	s_setprio 0
	s_add_i32 s56, s56, 2
	s_add_u32 s16, s16, 0x100
	s_addc_u32 s17, s17, 0
	s_cmp_gt_u32 s56, 11
	s_barrier
	s_cbranch_scc0 .LBB0_468
	s_lshl_b64 s[14:15], s[14:15], 1
	s_add_u32 s14, s42, s14
	s_addc_u32 s15, s43, s15
	s_mov_b32 m0, s40
	ds_read_b128 v[142:145], v137
	ds_read_b128 v[146:149], v137 offset:1024
	ds_read_b128 v[150:153], v137 offset:2048
	ds_read_b128 v[154:157], v137 offset:3072
	ds_read_b128 v[158:161], v136
	ds_read_b128 v[162:165], v136 offset:1024
	ds_read_b128 v[166:169], v136 offset:2048
	ds_read_b128 v[170:173], v136 offset:3072
	ds_read_b128 v[174:177], v136 offset:4096
	ds_read_b128 v[178:181], v136 offset:5120
	ds_read_b128 v[182:185], v136 offset:6144
	ds_read_b128 v[186:189], v136 offset:7168
	s_nop 0
	global_load_lds_dwordx4 v130, s[14:15]
	s_mov_b32 m0, s41
	s_nop 0
	global_load_lds_dwordx4 v132, s[14:15]
	s_barrier
	s_waitcnt lgkmcnt(0)
	s_setprio 3
	s_waitcnt lgkmcnt(0)
	v_mfma_f32_16x16x32_bf16 v[30:33], v[158:161], v[142:145], v[30:33]
	v_mfma_f32_16x16x32_bf16 v[26:29], v[158:161], v[150:153], v[26:29]
	v_mfma_f32_16x16x32_bf16 v[22:25], v[166:169], v[142:145], v[22:25]
	v_mfma_f32_16x16x32_bf16 v[18:21], v[166:169], v[150:153], v[18:21]
	v_mfma_f32_16x16x32_bf16 v[14:17], v[174:177], v[142:145], v[14:17]
	v_mfma_f32_16x16x32_bf16 v[10:13], v[174:177], v[150:153], v[10:13]
	v_mfma_f32_16x16x32_bf16 v[6:9], v[182:185], v[142:145], v[6:9]
	v_mfma_f32_16x16x32_bf16 v[2:5], v[182:185], v[150:153], v[2:5]
	v_mfma_f32_16x16x32_bf16 v[30:33], v[162:165], v[146:149], v[30:33]
	v_mfma_f32_16x16x32_bf16 v[26:29], v[162:165], v[154:157], v[26:29]
	v_mfma_f32_16x16x32_bf16 v[22:25], v[170:173], v[146:149], v[22:25]
	v_mfma_f32_16x16x32_bf16 v[18:21], v[170:173], v[154:157], v[18:21]
	v_mfma_f32_16x16x32_bf16 v[14:17], v[178:181], v[146:149], v[14:17]
	v_mfma_f32_16x16x32_bf16 v[10:13], v[178:181], v[154:157], v[10:13]
	v_mfma_f32_16x16x32_bf16 v[6:9], v[186:189], v[146:149], v[6:9]
	v_mfma_f32_16x16x32_bf16 v[2:5], v[186:189], v[154:157], v[2:5]
	s_setprio 0
	s_barrier
	ds_read_b128 v[190:193], v137 offset:16384
	ds_read_b128 v[194:197], v137 offset:17408
	ds_read_b128 v[198:201], v137 offset:18432
	ds_read_b128 v[202:205], v137 offset:19456
	s_barrier
	s_waitcnt lgkmcnt(0)
	s_setprio 3
	s_waitcnt lgkmcnt(0)
	v_mfma_f32_16x16x32_bf16 v[62:65], v[158:161], v[190:193], v[62:65]
	v_mfma_f32_16x16x32_bf16 v[58:61], v[158:161], v[198:201], v[58:61]
	v_mfma_f32_16x16x32_bf16 v[54:57], v[166:169], v[190:193], v[54:57]
	v_mfma_f32_16x16x32_bf16 v[50:53], v[166:169], v[198:201], v[50:53]
	v_mfma_f32_16x16x32_bf16 v[46:49], v[174:177], v[190:193], v[46:49]
	v_mfma_f32_16x16x32_bf16 v[42:45], v[174:177], v[198:201], v[42:45]
	v_mfma_f32_16x16x32_bf16 v[38:41], v[182:185], v[190:193], v[38:41]
	v_mfma_f32_16x16x32_bf16 v[34:37], v[182:185], v[198:201], v[34:37]
	v_mfma_f32_16x16x32_bf16 v[62:65], v[162:165], v[194:197], v[62:65]
	v_mfma_f32_16x16x32_bf16 v[58:61], v[162:165], v[202:205], v[58:61]
	v_mfma_f32_16x16x32_bf16 v[54:57], v[170:173], v[194:197], v[54:57]
	v_mfma_f32_16x16x32_bf16 v[50:53], v[170:173], v[202:205], v[50:53]
	v_mfma_f32_16x16x32_bf16 v[46:49], v[178:181], v[194:197], v[46:49]
	v_mfma_f32_16x16x32_bf16 v[42:45], v[178:181], v[202:205], v[42:45]
	v_mfma_f32_16x16x32_bf16 v[38:41], v[186:189], v[194:197], v[38:41]
	v_mfma_f32_16x16x32_bf16 v[34:37], v[186:189], v[202:205], v[34:37]
	s_setprio 0
	s_barrier
	ds_read_b128 v[158:161], v136 offset:16384
	ds_read_b128 v[162:165], v136 offset:17408
	ds_read_b128 v[166:169], v136 offset:18432
	ds_read_b128 v[170:173], v136 offset:19456
	ds_read_b128 v[174:177], v136 offset:20480
	ds_read_b128 v[178:181], v136 offset:21504
	ds_read_b128 v[182:185], v136 offset:22528
	ds_read_b128 v[186:189], v136 offset:23552
	s_waitcnt vmcnt(4)
	s_barrier
	s_waitcnt lgkmcnt(0)
	s_setprio 3
	s_waitcnt lgkmcnt(0)
	v_mfma_f32_16x16x32_bf16 v[94:97], v[158:161], v[142:145], v[94:97]
	v_mfma_f32_16x16x32_bf16 v[90:93], v[158:161], v[150:153], v[90:93]
	v_mfma_f32_16x16x32_bf16 v[86:89], v[166:169], v[142:145], v[86:89]
	v_mfma_f32_16x16x32_bf16 v[82:85], v[166:169], v[150:153], v[82:85]
	v_mfma_f32_16x16x32_bf16 v[78:81], v[174:177], v[142:145], v[78:81]
	v_mfma_f32_16x16x32_bf16 v[74:77], v[174:177], v[150:153], v[74:77]
	v_mfma_f32_16x16x32_bf16 v[70:73], v[182:185], v[142:145], v[70:73]
	v_mfma_f32_16x16x32_bf16 v[66:69], v[182:185], v[150:153], v[66:69]
	v_mfma_f32_16x16x32_bf16 v[216:219], v[162:165], v[146:149], v[94:97]
	v_mfma_f32_16x16x32_bf16 v[220:223], v[162:165], v[154:157], v[90:93]
	v_mfma_f32_16x16x32_bf16 v[224:227], v[170:173], v[146:149], v[86:89]
	v_mfma_f32_16x16x32_bf16 v[228:231], v[170:173], v[154:157], v[82:85]
	v_mfma_f32_16x16x32_bf16 v[232:235], v[178:181], v[146:149], v[78:81]
	v_mfma_f32_16x16x32_bf16 v[236:239], v[178:181], v[154:157], v[74:77]
	v_mfma_f32_16x16x32_bf16 v[142:145], v[186:189], v[146:149], v[70:73]
	v_mfma_f32_16x16x32_bf16 v[146:149], v[186:189], v[154:157], v[66:69]
	s_setprio 0
	s_setprio 3
	v_mfma_f32_16x16x32_bf16 v[66:69], v[158:161], v[190:193], v[126:129]
	v_mfma_f32_16x16x32_bf16 v[150:153], v[162:165], v[194:197], v[66:69]
	v_mfma_f32_16x16x32_bf16 v[66:69], v[158:161], v[198:201], v[122:125]
	v_mfma_f32_16x16x32_bf16 v[154:157], v[162:165], v[202:205], v[66:69]
	v_mfma_f32_16x16x32_bf16 v[66:69], v[166:169], v[190:193], v[118:121]
	v_mfma_f32_16x16x32_bf16 v[158:161], v[170:173], v[194:197], v[66:69]
	v_mfma_f32_16x16x32_bf16 v[66:69], v[166:169], v[198:201], v[114:117]
	v_mfma_f32_16x16x32_bf16 v[162:165], v[170:173], v[202:205], v[66:69]
	v_mfma_f32_16x16x32_bf16 v[66:69], v[174:177], v[190:193], v[110:113]
	v_mfma_f32_16x16x32_bf16 v[166:169], v[178:181], v[194:197], v[66:69]
	v_mfma_f32_16x16x32_bf16 v[66:69], v[174:177], v[198:201], v[106:109]
	v_mfma_f32_16x16x32_bf16 v[170:173], v[178:181], v[202:205], v[66:69]
	v_mfma_f32_16x16x32_bf16 v[66:69], v[182:185], v[190:193], v[102:105]
	v_mfma_f32_16x16x32_bf16 v[174:177], v[186:189], v[194:197], v[66:69]
	v_mfma_f32_16x16x32_bf16 v[66:69], v[182:185], v[198:201], v[98:101]
	v_mfma_f32_16x16x32_bf16 v[178:181], v[186:189], v[202:205], v[66:69]
	s_setprio 0
	s_barrier
	ds_read_b128 v[182:185], v137 offset:32768
	ds_read_b128 v[186:189], v137 offset:33792
	ds_read_b128 v[190:193], v137 offset:34816
	ds_read_b128 v[194:197], v137 offset:35840
	ds_read_b128 v[74:77], v136 offset:32768
	ds_read_b128 v[78:81], v136 offset:33792
	ds_read_b128 v[90:93], v136 offset:34816
	ds_read_b128 v[94:97], v136 offset:35840
	ds_read_b128 v[198:201], v136 offset:36864
	ds_read_b128 v[202:205], v136 offset:37888
	ds_read_b128 v[240:243], v136 offset:38912
	ds_read_b128 v[244:247], v136 offset:39936
	s_waitcnt vmcnt(2)
	s_barrier
	s_waitcnt lgkmcnt(0)
	s_setprio 3
	s_waitcnt lgkmcnt(0)
	v_mfma_f32_16x16x32_bf16 v[30:33], v[74:77], v[182:185], v[30:33]
	v_mfma_f32_16x16x32_bf16 v[26:29], v[74:77], v[190:193], v[26:29]
	v_mfma_f32_16x16x32_bf16 v[22:25], v[90:93], v[182:185], v[22:25]
	v_mfma_f32_16x16x32_bf16 v[18:21], v[90:93], v[190:193], v[18:21]
	v_mfma_f32_16x16x32_bf16 v[14:17], v[198:201], v[182:185], v[14:17]
	v_mfma_f32_16x16x32_bf16 v[10:13], v[198:201], v[190:193], v[10:13]
	v_mfma_f32_16x16x32_bf16 v[6:9], v[240:243], v[182:185], v[6:9]
	v_mfma_f32_16x16x32_bf16 v[2:5], v[240:243], v[190:193], v[2:5]
	v_mfma_f32_16x16x32_bf16 v[118:121], v[78:81], v[186:189], v[30:33]
	v_mfma_f32_16x16x32_bf16 v[114:117], v[78:81], v[194:197], v[26:29]
	v_mfma_f32_16x16x32_bf16 v[102:105], v[94:97], v[186:189], v[22:25]
	v_mfma_f32_16x16x32_bf16 v[98:101], v[94:97], v[194:197], v[18:21]
	v_mfma_f32_16x16x32_bf16 v[86:89], v[202:205], v[186:189], v[14:17]
	v_mfma_f32_16x16x32_bf16 v[82:85], v[202:205], v[194:197], v[10:13]
	v_mfma_f32_16x16x32_bf16 v[70:73], v[244:247], v[186:189], v[6:9]
	v_mfma_f32_16x16x32_bf16 v[66:69], v[244:247], v[194:197], v[2:5]
	s_setprio 0
	s_barrier
	ds_read_b128 v[10:13], v137 offset:49152
	ds_read_b128 v[14:17], v137 offset:50176
	ds_read_b128 v[248:251], v137 offset:51200
	ds_read_b128 v[138:141], v137 offset:52224
	s_waitcnt vmcnt(0)
	s_barrier
	s_waitcnt lgkmcnt(0)
	s_setprio 3
	s_waitcnt lgkmcnt(0)
	v_mfma_f32_16x16x32_bf16 v[2:5], v[74:77], v[10:13], v[62:65]
	v_mfma_f32_16x16x32_bf16 v[126:129], v[78:81], v[14:17], v[2:5]
	v_mfma_f32_16x16x32_bf16 v[2:5], v[74:77], v[248:251], v[58:61]
	v_mfma_f32_16x16x32_bf16 v[122:125], v[78:81], v[138:141], v[2:5]
	v_mfma_f32_16x16x32_bf16 v[2:5], v[90:93], v[10:13], v[54:57]
	v_mfma_f32_16x16x32_bf16 v[110:113], v[94:97], v[14:17], v[2:5]
	v_mfma_f32_16x16x32_bf16 v[2:5], v[90:93], v[248:251], v[50:53]
	v_mfma_f32_16x16x32_bf16 v[106:109], v[94:97], v[138:141], v[2:5]
	v_mfma_f32_16x16x32_bf16 v[2:5], v[198:201], v[10:13], v[46:49]
	v_mfma_f32_16x16x32_bf16 v[94:97], v[202:205], v[14:17], v[2:5]
	v_mfma_f32_16x16x32_bf16 v[2:5], v[198:201], v[248:251], v[42:45]
	v_mfma_f32_16x16x32_bf16 v[90:93], v[202:205], v[138:141], v[2:5]
	v_mfma_f32_16x16x32_bf16 v[2:5], v[240:243], v[10:13], v[38:41]
	v_mfma_f32_16x16x32_bf16 v[78:81], v[244:247], v[14:17], v[2:5]
	v_mfma_f32_16x16x32_bf16 v[2:5], v[240:243], v[248:251], v[34:37]
	v_mfma_f32_16x16x32_bf16 v[74:77], v[244:247], v[138:141], v[2:5]
	s_setprio 0
	s_barrier
	ds_read_b128 v[26:29], v136 offset:49152
	ds_read_b128 v[30:33], v136 offset:50176
	ds_read_b128 v[42:45], v136 offset:51200
	ds_read_b128 v[198:201], v136 offset:52224
	ds_read_b128 v[202:205], v136 offset:53248
	ds_read_b128 v[240:243], v136 offset:54272
	ds_read_b128 v[244:247], v136 offset:55296
	ds_read_b128 v[212:215], v136 offset:56320
	s_barrier
	s_waitcnt lgkmcnt(0)
	s_setprio 3
	s_waitcnt lgkmcnt(0)
	v_mfma_f32_16x16x32_bf16 v[2:5], v[26:29], v[182:185], v[216:219]
	v_mfma_f32_16x16x32_bf16 v[54:57], v[30:33], v[186:189], v[2:5]
	v_mfma_f32_16x16x32_bf16 v[2:5], v[26:29], v[190:193], v[220:223]
	v_mfma_f32_16x16x32_bf16 v[50:53], v[30:33], v[194:197], v[2:5]
	v_mfma_f32_16x16x32_bf16 v[2:5], v[42:45], v[182:185], v[224:227]
	v_mfma_f32_16x16x32_bf16 v[38:41], v[198:201], v[186:189], v[2:5]
	v_mfma_f32_16x16x32_bf16 v[2:5], v[42:45], v[190:193], v[228:231]
	v_mfma_f32_16x16x32_bf16 v[34:37], v[198:201], v[194:197], v[2:5]
	v_mfma_f32_16x16x32_bf16 v[2:5], v[202:205], v[182:185], v[232:235]
	v_mfma_f32_16x16x32_bf16 v[22:25], v[240:243], v[186:189], v[2:5]
	v_mfma_f32_16x16x32_bf16 v[2:5], v[202:205], v[190:193], v[236:239]
	v_mfma_f32_16x16x32_bf16 v[18:21], v[240:243], v[194:197], v[2:5]
	v_mfma_f32_16x16x32_bf16 v[2:5], v[244:247], v[182:185], v[142:145]
	v_mfma_f32_16x16x32_bf16 v[6:9], v[212:215], v[186:189], v[2:5]
	v_mfma_f32_16x16x32_bf16 v[2:5], v[244:247], v[190:193], v[146:149]
	v_mfma_f32_16x16x32_bf16 v[2:5], v[212:215], v[194:197], v[2:5]
	s_setprio 0
	s_setprio 3
	v_mfma_f32_16x16x32_bf16 v[46:49], v[26:29], v[10:13], v[150:153]
	v_mfma_f32_16x16x32_bf16 v[26:29], v[26:29], v[248:251], v[154:157]
	v_mfma_f32_16x16x32_bf16 v[58:61], v[30:33], v[138:141], v[26:29]
	v_mfma_f32_16x16x32_bf16 v[26:29], v[42:45], v[10:13], v[158:161]
	v_mfma_f32_16x16x32_bf16 v[62:65], v[30:33], v[14:17], v[46:49]
	v_mfma_f32_16x16x32_bf16 v[46:49], v[198:201], v[14:17], v[26:29]
	v_mfma_f32_16x16x32_bf16 v[26:29], v[42:45], v[248:251], v[162:165]
	v_mfma_f32_16x16x32_bf16 v[42:45], v[198:201], v[138:141], v[26:29]
	v_mfma_f32_16x16x32_bf16 v[26:29], v[202:205], v[10:13], v[166:169]
	v_mfma_f32_16x16x32_bf16 v[10:13], v[244:247], v[10:13], v[174:177]
	v_mfma_f32_16x16x32_bf16 v[30:33], v[240:243], v[14:17], v[26:29]
	v_mfma_f32_16x16x32_bf16 v[26:29], v[202:205], v[248:251], v[170:173]
	v_mfma_f32_16x16x32_bf16 v[14:17], v[212:215], v[14:17], v[10:13]
	v_mfma_f32_16x16x32_bf16 v[10:13], v[244:247], v[248:251], v[178:181]
	v_mfma_f32_16x16x32_bf16 v[26:29], v[240:243], v[138:141], v[26:29]
	v_mfma_f32_16x16x32_bf16 v[10:13], v[212:215], v[138:141], v[10:13]
	s_setprio 0
	s_and_b64 vcc, exec, s[10:11]
	s_barrier
	s_cbranch_vccz .LBB0_471
	s_barrier
